# fused-epilogue row-statistic cross-lane reduction: ds_bpermute (lane xor 16/32) replaced by v_permlane16_swap/v_permlane32_swap, on top of previous stack
# speedup vs baseline: 1.0015x; 1.0015x over previous
.LBB0_107:
	global_load_dwordx4 v[30:33], v59, s[18:19]
	global_load_dwordx4 v[26:29], v59, s[18:19] offset:1024
	global_load_dwordx4 v[22:25], v59, s[18:19] offset:2048
	global_load_dwordx4 v[10:13], v60, s[18:19]
	global_load_dwordx4 v[18:21], v59, s[18:19] offset:3072
	global_load_dwordx4 v[14:17], v61, s[18:19]
	global_load_dwordx4 v[2:5], v63, s[18:19]
	global_load_dwordx4 v[6:9], v62, s[18:19]
	global_load_dwordx4 v[74:77], v[36:37], off
	s_lshl_b64 s[18:19], s[4:5], 12
	s_add_u32 s18, s28, s18
	s_addc_u32 s19, s29, s19
	s_add_i32 s24, s24, 8
	s_add_u32 s14, s14, 8
	s_addc_u32 s15, s15, 0
	s_add_u32 s16, s16, 0x10000
	s_addc_u32 s17, s17, 0
	s_cmp_lt_i32 s24, s25
	s_waitcnt vmcnt(8)
	v_mov_b32_e32 v80, v31
	s_waitcnt vmcnt(7)
	v_mov_b32_e32 v81, v27
	v_mov_b32_e32 v84, v33
	v_mov_b32_e32 v85, v29
	v_mov_b32_e32 v78, v30
	v_mov_b32_e32 v79, v26
	v_mov_b32_e32 v82, v32
	v_mov_b32_e32 v83, v28
	s_waitcnt vmcnt(6)
	v_pk_mul_f32 v[86:87], v[24:25], v[24:25]
	v_pk_mul_f32 v[88:89], v[22:23], v[22:23]
	v_pk_mul_f32 v[80:81], v[80:81], v[80:81]
	v_pk_mul_f32 v[84:85], v[84:85], v[84:85]
	v_pk_mov_b32 v[102:103], v[88:89], v[86:87] op_sel:[1,0]
	v_mov_b32_e32 v89, v87
	v_pk_fma_f32 v[78:79], v[78:79], v[78:79], v[80:81]
	v_pk_fma_f32 v[80:81], v[82:83], v[82:83], v[84:85]
	s_waitcnt vmcnt(4)
	v_mul_f32_e32 v90, v19, v19
	v_mul_f32_e32 v92, v21, v21
	v_pk_add_f32 v[82:83], v[102:103], v[88:89]
	v_pk_add_f32 v[78:79], v[78:79], v[80:81]
	v_mul_f32_e32 v101, v10, v10
	v_mul_f32_e32 v104, v11, v11
	v_mul_f32_e32 v105, v12, v12
	v_mul_f32_e32 v106, v13, v13
	v_pk_fma_f32 v[86:87], v[18:19], v[18:19], v[90:91] op_sel_hi:[1,1,0]
	v_pk_fma_f32 v[90:91], v[20:21], v[20:21], v[92:93] op_sel_hi:[1,1,0]
	v_pk_add_f32 v[80:81], v[82:83], v[82:83] op_sel:[0,1] op_sel_hi:[1,0]
	v_pk_add_f32 v[78:79], v[78:79], v[78:79] op_sel:[0,1] op_sel_hi:[1,0]
	s_waitcnt vmcnt(3)
	v_pk_mul_f32 v[94:95], v[16:17], v[16:17]
	v_pk_mul_f32 v[96:97], v[14:15], v[14:15]
	v_mov_b32_e32 v87, v105
	v_mov_b32_e32 v91, v106
	v_mov_b32_e32 v81, v104
	v_mov_b32_e32 v79, v101
	v_pk_mov_b32 v[92:93], v[96:97], v[94:95] op_sel:[1,0]
	v_mov_b32_e32 v97, v95
	v_pk_add_f32 v[82:83], v[86:87], v[90:91]
	v_pk_add_f32 v[78:79], v[78:79], v[80:81]
	s_waitcnt vmcnt(1)
	v_mul_f32_e32 v98, v7, v7
	v_mul_f32_e32 v100, v9, v9
	v_pk_add_f32 v[84:85], v[92:93], v[96:97]
	v_pk_add_f32 v[78:79], v[78:79], v[82:83]
	v_mul_f32_e32 v107, v2, v2
	v_mul_f32_e32 v108, v3, v3
	v_mul_f32_e32 v109, v4, v4
	v_mul_f32_e32 v110, v5, v5
	v_pk_fma_f32 v[94:95], v[6:7], v[6:7], v[98:99] op_sel_hi:[1,1,0]
	v_pk_fma_f32 v[98:99], v[8:9], v[8:9], v[100:101] op_sel_hi:[1,1,0]
	v_pk_add_f32 v[84:85], v[84:85], v[84:85] op_sel:[0,1] op_sel_hi:[1,0]
	v_pk_add_f32 v[78:79], v[78:79], v[78:79] op_sel:[0,1] op_sel_hi:[1,0]
	v_mov_b32_e32 v95, v109
	v_mov_b32_e32 v99, v110
	v_mov_b32_e32 v85, v108
	v_mov_b32_e32 v79, v107
	v_pk_add_f32 v[86:87], v[94:95], v[98:99]
	v_pk_add_f32 v[78:79], v[78:79], v[84:85]
	s_nop 0
	v_pk_add_f32 v[78:79], v[78:79], v[86:87]
	s_nop 0
	v_add_f32_e32 v78, v78, v79
	ds_bpermute_b32 v79, v35, v78
	s_waitcnt lgkmcnt(0)
	v_add_f32_e32 v78, v78, v79
	ds_bpermute_b32 v79, v46, v78
	s_waitcnt lgkmcnt(0)
	v_add_f32_e32 v78, v78, v79
	ds_bpermute_b32 v79, v47, v78
	s_waitcnt lgkmcnt(0)
	v_add_f32_e32 v78, v78, v79
	ds_bpermute_b32 v79, v48, v78
	s_waitcnt lgkmcnt(0)
	v_add_f32_e32 v78, v78, v79
	v_mov_b32_e32 v79, v78
	s_nop 1
	v_permlane16_swap_b32 v79, v78
	s_nop 1
	s_waitcnt lgkmcnt(0)
	v_add_f32_e32 v78, v78, v79
	v_mov_b32_e32 v79, v78
	s_nop 1
	v_permlane32_swap_b32 v79, v78
	s_nop 1
	s_waitcnt lgkmcnt(0)
	v_add_f32_e32 v78, v78, v79
	v_fmamk_f32 v78, v78, 0x3a000000, v64
	v_mul_f32_e32 v79, 0x4f800000, v78
	v_cmp_gt_f32_e32 vcc, s30, v78
	s_nop 1
	v_cndmask_b32_e32 v86, v78, v79, vcc
	v_sqrt_f32_e32 v87, v86
	ds_read_b128 v[78:81], v51 offset:8192
	ds_read_b128 v[82:85], v51
	v_add_u32_e32 v88, -1, v87
	v_add_u32_e32 v89, 1, v87
	v_fma_f32 v90, -v88, v87, v86
	v_fma_f32 v91, -v89, v87, v86
	v_cmp_ge_f32_e64 s[4:5], 0, v90
	s_nop 1
	v_cndmask_b32_e64 v87, v87, v88, s[4:5]
	v_cmp_lt_f32_e64 s[4:5], 0, v91
	s_nop 1
	v_cndmask_b32_e64 v87, v87, v89, s[4:5]
	v_mul_f32_e32 v88, 0x37800000, v87
	v_cndmask_b32_e32 v87, v87, v88, vcc
	v_cmp_class_f32_e32 vcc, v86, v65
	s_nop 1
	v_cndmask_b32_e32 v86, v87, v86, vcc
	v_div_scale_f32 v87, s[4:5], v86, v86, 1.0
	v_rcp_f32_e32 v88, v87
	v_div_scale_f32 v89, vcc, 1.0, v86, 1.0
	v_fma_f32 v90, -v87, v88, 1.0
	v_fmac_f32_e32 v88, v90, v88
	v_mul_f32_e32 v90, v89, v88
	v_fma_f32 v91, -v87, v90, v89
	v_fmac_f32_e32 v90, v91, v88
	v_fma_f32 v87, -v87, v90, v89
	v_div_fmas_f32 v87, v87, v88, v90
	v_div_fixup_f32 v86, v87, v86, 1.0
	v_pk_mul_f32 v[30:31], v[30:31], v[86:87] op_sel_hi:[1,0]
	v_pk_mul_f32 v[32:33], v[32:33], v[86:87] op_sel_hi:[1,0]
	s_waitcnt vmcnt(0)
	v_pk_mul_f32 v[30:31], v[74:75], v[30:31]
	v_pk_mul_f32 v[32:33], v[76:77], v[32:33]
	s_waitcnt lgkmcnt(0)
	v_pk_fma_f32 v[30:31], v[78:79], v[30:31], v[82:83]
	v_pk_fma_f32 v[32:33], v[80:81], v[32:33], v[84:85]
	v_cvt_pk_bf16_f32 v30, v30, v31
	v_pk_mul_f32 v[26:27], v[26:27], v[86:87] op_sel_hi:[1,0]
	v_cvt_pk_bf16_f32 v31, v32, v33
	global_store_dwordx2 v66, v[30:31], s[18:19]
	global_load_dwordx4 v[30:33], v[36:37], off offset:1024
	ds_read_b128 v[74:77], v52 offset:8192
	ds_read_b128 v[78:81], v52
	v_pk_mul_f32 v[28:29], v[28:29], v[86:87] op_sel_hi:[1,0]
	v_pk_mul_f32 v[22:23], v[22:23], v[86:87] op_sel_hi:[1,0]
	v_pk_mul_f32 v[24:25], v[24:25], v[86:87] op_sel_hi:[1,0]
	v_pk_mul_f32 v[18:19], v[18:19], v[86:87] op_sel_hi:[1,0]
	v_pk_mul_f32 v[20:21], v[20:21], v[86:87] op_sel_hi:[1,0]
	v_pk_mul_f32 v[10:11], v[10:11], v[86:87] op_sel_hi:[1,0]
	v_pk_mul_f32 v[12:13], v[12:13], v[86:87] op_sel_hi:[1,0]
	v_pk_mul_f32 v[14:15], v[14:15], v[86:87] op_sel_hi:[1,0]
	v_pk_mul_f32 v[16:17], v[16:17], v[86:87] op_sel_hi:[1,0]
	v_pk_mul_f32 v[6:7], v[6:7], v[86:87] op_sel_hi:[1,0]
	v_pk_mul_f32 v[8:9], v[8:9], v[86:87] op_sel_hi:[1,0]
	v_pk_mul_f32 v[2:3], v[2:3], v[86:87] op_sel_hi:[1,0]
	v_pk_mul_f32 v[4:5], v[4:5], v[86:87] op_sel_hi:[1,0]
	s_waitcnt vmcnt(0)
	v_pk_mul_f32 v[26:27], v[30:31], v[26:27]
	v_pk_mul_f32 v[28:29], v[32:33], v[28:29]
	s_waitcnt lgkmcnt(0)
	v_pk_fma_f32 v[26:27], v[74:75], v[26:27], v[78:79]
	v_pk_fma_f32 v[28:29], v[76:77], v[28:29], v[80:81]
	v_cvt_pk_bf16_f32 v26, v26, v27
	s_nop 0
	v_cvt_pk_bf16_f32 v27, v28, v29
	global_store_dwordx2 v67, v[26:27], s[18:19]
	global_load_dwordx4 v[26:29], v[36:37], off offset:2048
	ds_read_b128 v[30:33], v53 offset:8192
	ds_read_b128 v[74:77], v53
	s_waitcnt vmcnt(0)
	v_pk_mul_f32 v[22:23], v[22:23], v[26:27]
	v_pk_mul_f32 v[24:25], v[24:25], v[28:29]
	s_waitcnt lgkmcnt(0)
	v_pk_fma_f32 v[22:23], v[22:23], v[30:31], v[74:75]
	v_pk_fma_f32 v[24:25], v[24:25], v[32:33], v[76:77]
	v_cvt_pk_bf16_f32 v22, v22, v23
	s_nop 0
	v_cvt_pk_bf16_f32 v23, v24, v25
	global_store_dwordx2 v68, v[22:23], s[18:19]
	global_load_dwordx4 v[22:25], v[36:37], off offset:3072
	ds_read_b128 v[26:29], v54 offset:8192
	ds_read_b128 v[30:33], v54
	s_waitcnt vmcnt(0)
	v_pk_mul_f32 v[18:19], v[18:19], v[22:23]
	v_pk_mul_f32 v[20:21], v[20:21], v[24:25]
	s_waitcnt lgkmcnt(0)
	v_pk_fma_f32 v[18:19], v[18:19], v[26:27], v[30:31]
	v_pk_fma_f32 v[20:21], v[20:21], v[28:29], v[32:33]
	v_cvt_pk_bf16_f32 v18, v18, v19
	s_nop 0
	v_cvt_pk_bf16_f32 v19, v20, v21
	global_store_dwordx2 v69, v[18:19], s[18:19]
	global_load_dwordx4 v[18:21], v[38:39], off
	ds_read_b128 v[22:25], v55 offset:8192
	ds_read_b128 v[26:29], v55
	s_waitcnt vmcnt(0)
	v_pk_mul_f32 v[10:11], v[10:11], v[18:19]
	v_pk_mul_f32 v[12:13], v[12:13], v[20:21]
	s_waitcnt lgkmcnt(0)
	v_pk_fma_f32 v[10:11], v[10:11], v[22:23], v[26:27]
	v_pk_fma_f32 v[12:13], v[12:13], v[24:25], v[28:29]
	v_cvt_pk_bf16_f32 v10, v10, v11
	s_nop 0
	v_cvt_pk_bf16_f32 v11, v12, v13
	global_store_dwordx2 v70, v[10:11], s[18:19]
	global_load_dwordx4 v[10:13], v[40:41], off
	ds_read_b128 v[18:21], v56 offset:8192
	ds_read_b128 v[22:25], v56
	s_waitcnt vmcnt(0)
	v_pk_mul_f32 v[10:11], v[14:15], v[10:11]
	v_pk_mul_f32 v[12:13], v[16:17], v[12:13]
	s_waitcnt lgkmcnt(0)
	v_pk_fma_f32 v[10:11], v[10:11], v[18:19], v[22:23]
	v_pk_fma_f32 v[12:13], v[12:13], v[20:21], v[24:25]
	v_cvt_pk_bf16_f32 v10, v10, v11
	s_nop 0
	v_cvt_pk_bf16_f32 v11, v12, v13
	global_store_dwordx2 v71, v[10:11], s[18:19]
	global_load_dwordx4 v[10:13], v[42:43], off
	ds_read_b128 v[14:17], v57 offset:8192
	ds_read_b128 v[18:21], v57
	s_waitcnt vmcnt(0)
	v_pk_mul_f32 v[6:7], v[6:7], v[10:11]
	v_pk_mul_f32 v[8:9], v[8:9], v[12:13]
	s_waitcnt lgkmcnt(0)
	v_pk_fma_f32 v[6:7], v[6:7], v[14:15], v[18:19]
	v_pk_fma_f32 v[8:9], v[8:9], v[16:17], v[20:21]
	v_cvt_pk_bf16_f32 v6, v6, v7
	s_nop 0
	v_cvt_pk_bf16_f32 v7, v8, v9
	global_store_dwordx2 v72, v[6:7], s[18:19]
	global_load_dwordx4 v[6:9], v[44:45], off
	ds_read_b128 v[10:13], v58 offset:8192
	ds_read_b128 v[14:17], v58
	s_waitcnt vmcnt(0)
	v_pk_mul_f32 v[2:3], v[2:3], v[6:7]
	v_pk_mul_f32 v[4:5], v[4:5], v[8:9]
	s_waitcnt lgkmcnt(0)
	v_pk_fma_f32 v[2:3], v[2:3], v[10:11], v[14:15]
	v_pk_fma_f32 v[4:5], v[4:5], v[12:13], v[16:17]
	v_cvt_pk_bf16_f32 v2, v2, v3
	s_nop 0
	v_cvt_pk_bf16_f32 v3, v4, v5
	global_store_dwordx2 v73, v[2:3], s[18:19]
	s_cbranch_scc0 .LBB0_110

.LBB0_200:
	s_lshl_b32 s26, s16, 8
	s_lshl_b32 s30, s83, 5
	s_add_i32 s31, s26, s33
	s_cmp_gt_i32 s16, 15
	s_cselect_b64 s[24:25], -1, 0
	s_cmp_lt_i32 s16, 16
	v_bfe_u32 v191, v190, 4, 2
	v_or_b32_e32 v2, s31, v189
	s_cselect_b64 s[16:17], -1, 0
	s_cmp_eq_u32 s22, 4
	s_mov_b64 s[6:7], -1
	s_barrier
	s_cbranch_scc1 .LBB0_264
	v_mul_f32_e32 v133, v65, v65
	v_mul_f32_e32 v134, v67, v67
	v_fmac_f32_e32 v133, v64, v64
	v_fmac_f32_e32 v134, v66, v66
	v_add_f32_e32 v133, v133, v134
	v_mul_f32_e32 v134, v61, v61
	v_mul_f32_e32 v135, v63, v63
	v_fmac_f32_e32 v134, v60, v60
	v_fmac_f32_e32 v135, v62, v62
	v_add_f32_e32 v134, v134, v135
	v_add_f32_e32 v133, v134, v133
	v_mul_f32_e32 v134, v129, v129
	v_mul_f32_e32 v135, v131, v131
	v_fmac_f32_e32 v134, v128, v128
	v_fmac_f32_e32 v135, v130, v130
	v_add_f32_e32 v134, v134, v135
	v_add_f32_e32 v133, v134, v133
	v_mul_f32_e32 v134, v125, v125
	v_mul_f32_e32 v135, v127, v127
	v_and_b32_e32 v0, 63, v190
	v_fmac_f32_e32 v134, v124, v124
	v_fmac_f32_e32 v135, v126, v126
	v_lshlrev_b32_e32 v132, 2, v0
	v_add_f32_e32 v134, v134, v135
	v_xor_b32_e32 v3, 64, v132
	v_add_f32_e32 v134, v134, v133
	v_mov_b32_e32 v135, v134
	s_nop 1
	v_permlane16_swap_b32 v135, v134
	s_nop 1
	v_xor_b32_e32 v133, 0x80, v132
	s_lshl_b32 s6, s83, 2
	s_add_i32 s6, s6, 0
	v_cmp_gt_u32_e32 vcc, 16, v0
	s_waitcnt lgkmcnt(0)
	v_add_f32_e32 v134, v134, v135
	v_mov_b32_e32 v135, v134
	s_nop 1
	v_permlane32_swap_b32 v135, v134
	s_nop 1
	v_lshl_add_u32 v132, v142, 4, s6
	s_and_saveexec_b64 s[6:7], vcc
	s_cbranch_execz .LBB0_203
	s_waitcnt lgkmcnt(0)
	v_add_f32_e32 v134, v134, v135
	ds_write_b32 v132, v134
.LBB0_203:
	s_or_b64 exec, exec, s[6:7]
	v_mul_f32_e32 v134, v57, v57
	s_waitcnt lgkmcnt(0)
	v_mul_f32_e32 v135, v59, v59
	v_fmac_f32_e32 v134, v56, v56
	v_fmac_f32_e32 v135, v58, v58
	v_add_f32_e32 v134, v134, v135
	v_mul_f32_e32 v135, v53, v53
	v_mul_f32_e32 v136, v55, v55
	v_fmac_f32_e32 v135, v52, v52
	v_fmac_f32_e32 v136, v54, v54
	v_add_f32_e32 v135, v135, v136
	v_add_f32_e32 v134, v135, v134
	v_mul_f32_e32 v135, v121, v121
	v_mul_f32_e32 v136, v123, v123
	v_fmac_f32_e32 v135, v120, v120
	v_fmac_f32_e32 v136, v122, v122
	v_add_f32_e32 v135, v135, v136
	v_add_f32_e32 v134, v135, v134
	v_mul_f32_e32 v135, v117, v117
	v_mul_f32_e32 v136, v119, v119
	v_fmac_f32_e32 v135, v116, v116
	v_fmac_f32_e32 v136, v118, v118
	v_add_f32_e32 v135, v135, v136
	v_add_f32_e32 v134, v135, v134
	v_mov_b32_e32 v135, v134
	s_nop 1
	v_permlane16_swap_b32 v135, v134
	s_nop 1
	s_waitcnt lgkmcnt(0)
	v_add_f32_e32 v134, v134, v135
	v_mov_b32_e32 v135, v134
	s_nop 1
	v_permlane32_swap_b32 v135, v134
	s_nop 1
	s_and_saveexec_b64 s[6:7], vcc
	s_cbranch_execz .LBB0_205
	s_waitcnt lgkmcnt(0)
	v_add_f32_e32 v134, v134, v135
	ds_write_b32 v132, v134 offset:256
.LBB0_205:
	s_or_b64 exec, exec, s[6:7]
	v_mul_f32_e32 v134, v49, v49
	s_waitcnt lgkmcnt(0)
	v_mul_f32_e32 v135, v51, v51
	v_fmac_f32_e32 v134, v48, v48
	v_fmac_f32_e32 v135, v50, v50
	v_add_f32_e32 v134, v134, v135
	v_mul_f32_e32 v135, v45, v45
	v_mul_f32_e32 v136, v47, v47
	v_fmac_f32_e32 v135, v44, v44
	v_fmac_f32_e32 v136, v46, v46
	v_add_f32_e32 v135, v135, v136
	v_add_f32_e32 v134, v135, v134
	v_mul_f32_e32 v135, v113, v113
	v_mul_f32_e32 v136, v115, v115
	v_fmac_f32_e32 v135, v112, v112
	v_fmac_f32_e32 v136, v114, v114
	v_add_f32_e32 v135, v135, v136
	v_add_f32_e32 v134, v135, v134
	v_mul_f32_e32 v135, v109, v109
	v_mul_f32_e32 v136, v111, v111
	v_fmac_f32_e32 v135, v108, v108
	v_fmac_f32_e32 v136, v110, v110
	v_add_f32_e32 v135, v135, v136
	v_add_f32_e32 v134, v135, v134
	v_mov_b32_e32 v135, v134
	s_nop 1
	v_permlane16_swap_b32 v135, v134
	s_nop 1
	s_waitcnt lgkmcnt(0)
	v_add_f32_e32 v134, v134, v135
	v_mov_b32_e32 v135, v134
	s_nop 1
	v_permlane32_swap_b32 v135, v134
	s_nop 1
	s_and_saveexec_b64 s[6:7], vcc
	s_cbranch_execz .LBB0_207
	s_waitcnt lgkmcnt(0)
	v_add_f32_e32 v134, v134, v135
	ds_write_b32 v132, v134 offset:512
.LBB0_207:
	s_or_b64 exec, exec, s[6:7]
	v_mul_f32_e32 v134, v41, v41
	s_waitcnt lgkmcnt(0)
	v_mul_f32_e32 v135, v43, v43
	v_fmac_f32_e32 v134, v40, v40
	v_fmac_f32_e32 v135, v42, v42
	v_add_f32_e32 v134, v134, v135
	v_mul_f32_e32 v135, v37, v37
	v_mul_f32_e32 v136, v39, v39
	v_fmac_f32_e32 v135, v36, v36
	v_fmac_f32_e32 v136, v38, v38
	v_add_f32_e32 v135, v135, v136
	v_add_f32_e32 v134, v135, v134
	v_mul_f32_e32 v135, v105, v105
	v_mul_f32_e32 v136, v107, v107
	v_fmac_f32_e32 v135, v104, v104
	v_fmac_f32_e32 v136, v106, v106
	v_add_f32_e32 v135, v135, v136
	v_add_f32_e32 v134, v135, v134
	v_mul_f32_e32 v135, v101, v101
	v_mul_f32_e32 v136, v103, v103
	v_fmac_f32_e32 v135, v100, v100
	v_fmac_f32_e32 v136, v102, v102
	v_add_f32_e32 v135, v135, v136
	v_add_f32_e32 v134, v135, v134
	v_mov_b32_e32 v135, v134
	s_nop 1
	v_permlane16_swap_b32 v135, v134
	s_nop 1
	s_waitcnt lgkmcnt(0)
	v_add_f32_e32 v134, v134, v135
	v_mov_b32_e32 v135, v134
	s_nop 1
	v_permlane32_swap_b32 v135, v134
	s_nop 1
	s_and_saveexec_b64 s[6:7], vcc
	s_cbranch_execz .LBB0_209
	s_waitcnt lgkmcnt(0)
	v_add_f32_e32 v134, v134, v135
	ds_write_b32 v132, v134 offset:768
.LBB0_209:
	s_or_b64 exec, exec, s[6:7]
	v_mul_f32_e32 v134, v33, v33
	s_waitcnt lgkmcnt(0)
	v_mul_f32_e32 v135, v35, v35
	v_fmac_f32_e32 v134, v32, v32
	v_fmac_f32_e32 v135, v34, v34
	v_add_f32_e32 v134, v134, v135
	v_mul_f32_e32 v135, v29, v29
	v_mul_f32_e32 v136, v31, v31
	v_fmac_f32_e32 v135, v28, v28
	v_fmac_f32_e32 v136, v30, v30
	v_add_f32_e32 v135, v135, v136
	v_add_f32_e32 v134, v135, v134
	v_mul_f32_e32 v135, v97, v97
	v_mul_f32_e32 v136, v99, v99
	v_fmac_f32_e32 v135, v96, v96
	v_fmac_f32_e32 v136, v98, v98
	v_add_f32_e32 v135, v135, v136
	v_add_f32_e32 v134, v135, v134
	v_mul_f32_e32 v135, v93, v93
	v_mul_f32_e32 v136, v95, v95
	v_fmac_f32_e32 v135, v92, v92
	v_fmac_f32_e32 v136, v94, v94
	v_add_f32_e32 v135, v135, v136
	v_add_f32_e32 v134, v135, v134
	v_mov_b32_e32 v135, v134
	s_nop 1
	v_permlane16_swap_b32 v135, v134
	s_nop 1
	s_waitcnt lgkmcnt(0)
	v_add_f32_e32 v134, v134, v135
	v_mov_b32_e32 v135, v134
	s_nop 1
	v_permlane32_swap_b32 v135, v134
	s_nop 1
	s_and_saveexec_b64 s[6:7], vcc
	s_cbranch_execz .LBB0_211
	s_waitcnt lgkmcnt(0)
	v_add_f32_e32 v134, v134, v135
	ds_write_b32 v132, v134 offset:2048
.LBB0_211:
	s_or_b64 exec, exec, s[6:7]
	v_mul_f32_e32 v134, v25, v25
	s_waitcnt lgkmcnt(0)
	v_mul_f32_e32 v135, v27, v27
	v_fmac_f32_e32 v134, v24, v24
	v_fmac_f32_e32 v135, v26, v26
	v_add_f32_e32 v134, v134, v135
	v_mul_f32_e32 v135, v21, v21
	v_mul_f32_e32 v136, v23, v23
	v_fmac_f32_e32 v135, v20, v20
	v_fmac_f32_e32 v136, v22, v22
	v_add_f32_e32 v135, v135, v136
	v_add_f32_e32 v134, v135, v134
	v_mul_f32_e32 v135, v89, v89
	v_mul_f32_e32 v136, v91, v91
	v_fmac_f32_e32 v135, v88, v88
	v_fmac_f32_e32 v136, v90, v90
	v_add_f32_e32 v135, v135, v136
	v_add_f32_e32 v134, v135, v134
	v_mul_f32_e32 v135, v85, v85
	v_mul_f32_e32 v136, v87, v87
	v_fmac_f32_e32 v135, v84, v84
	v_fmac_f32_e32 v136, v86, v86
	v_add_f32_e32 v135, v135, v136
	v_add_f32_e32 v134, v135, v134
	v_mov_b32_e32 v135, v134
	s_nop 1
	v_permlane16_swap_b32 v135, v134
	s_nop 1
	s_waitcnt lgkmcnt(0)
	v_add_f32_e32 v134, v134, v135
	v_mov_b32_e32 v135, v134
	s_nop 1
	v_permlane32_swap_b32 v135, v134
	s_nop 1
	s_and_saveexec_b64 s[6:7], vcc
	s_cbranch_execz .LBB0_213
	s_waitcnt lgkmcnt(0)
	v_add_f32_e32 v134, v134, v135
	ds_write_b32 v132, v134 offset:2304
.LBB0_213:
	s_or_b64 exec, exec, s[6:7]
	v_mul_f32_e32 v134, v17, v17
	s_waitcnt lgkmcnt(0)
	v_mul_f32_e32 v135, v19, v19
	v_fmac_f32_e32 v134, v16, v16
	v_fmac_f32_e32 v135, v18, v18
	v_add_f32_e32 v134, v134, v135
	v_mul_f32_e32 v135, v13, v13
	v_mul_f32_e32 v136, v15, v15
	v_fmac_f32_e32 v135, v12, v12
	v_fmac_f32_e32 v136, v14, v14
	v_add_f32_e32 v135, v135, v136
	v_add_f32_e32 v134, v135, v134
	v_mul_f32_e32 v135, v81, v81
	v_mul_f32_e32 v136, v83, v83
	v_fmac_f32_e32 v135, v80, v80
	v_fmac_f32_e32 v136, v82, v82
	v_add_f32_e32 v135, v135, v136
	v_add_f32_e32 v134, v135, v134
	v_mul_f32_e32 v135, v77, v77
	v_mul_f32_e32 v136, v79, v79
	v_fmac_f32_e32 v135, v76, v76
	v_fmac_f32_e32 v136, v78, v78
	v_add_f32_e32 v135, v135, v136
	v_add_f32_e32 v134, v135, v134
	v_mov_b32_e32 v135, v134
	s_nop 1
	v_permlane16_swap_b32 v135, v134
	s_nop 1
	s_waitcnt lgkmcnt(0)
	v_add_f32_e32 v134, v134, v135
	v_mov_b32_e32 v135, v134
	s_nop 1
	v_permlane32_swap_b32 v135, v134
	s_nop 1
	s_and_saveexec_b64 s[6:7], vcc
	s_cbranch_execz .LBB0_215
	s_waitcnt lgkmcnt(0)
	v_add_f32_e32 v134, v134, v135
	ds_write_b32 v132, v134 offset:2560
.LBB0_215:
	s_or_b64 exec, exec, s[6:7]
	v_mul_f32_e32 v134, v9, v9
	s_waitcnt lgkmcnt(0)
	v_mul_f32_e32 v135, v11, v11
	v_fmac_f32_e32 v134, v8, v8
	v_fmac_f32_e32 v135, v10, v10
	v_add_f32_e32 v134, v134, v135
	v_mul_f32_e32 v135, v5, v5
	v_mul_f32_e32 v136, v7, v7
	v_fmac_f32_e32 v135, v4, v4
	v_fmac_f32_e32 v136, v6, v6
	v_add_f32_e32 v135, v135, v136
	v_add_f32_e32 v134, v135, v134
	v_mul_f32_e32 v135, v73, v73
	v_mul_f32_e32 v136, v75, v75
	v_fmac_f32_e32 v135, v72, v72
	v_fmac_f32_e32 v136, v74, v74
	v_add_f32_e32 v135, v135, v136
	v_add_f32_e32 v134, v135, v134
	v_mul_f32_e32 v135, v69, v69
	v_mul_f32_e32 v136, v71, v71
	v_fmac_f32_e32 v135, v68, v68
	v_fmac_f32_e32 v136, v70, v70
	v_add_f32_e32 v135, v135, v136
	v_add_f32_e32 v134, v135, v134
	v_mov_b32_e32 v3, v134
	s_nop 1
	v_permlane16_swap_b32 v3, v134
	s_nop 1
	s_waitcnt lgkmcnt(0)
	v_add_f32_e32 v3, v134, v3
	v_mov_b32_e32 v133, v3
	s_nop 1
	v_permlane32_swap_b32 v133, v3
	s_nop 1
	s_and_saveexec_b64 s[6:7], vcc
	s_cbranch_execz .LBB0_217
	s_waitcnt lgkmcnt(0)
	v_add_f32_e32 v3, v3, v133
	ds_write_b32 v132, v3 offset:2816

.LBB0_894:
	s_add_u32 s6, s10, 0x15e12000
	s_addc_u32 s7, s11, 0
	s_add_u32 s21, s10, 0x16e12000
	s_mul_i32 s4, s56, 0x9000
	s_mov_b32 s5, s50
	s_addc_u32 s24, s11, 0
	s_lshl_b64 s[4:5], s[4:5], 2
	s_add_u32 s25, s10, s4
	s_addc_u32 s27, s11, s5
	s_lshl_b32 s4, s33, 5
	s_lshl_b32 s26, s20, 8
	s_lshl_b32 s28, s18, 8
	v_lshrrev_b32_e32 v0, 1, v212
	s_add_i32 s5, s26, s80
	s_or_b32 s4, s28, s4
	v_and_or_b32 v208, v0, 24, s4
	s_cmp_lt_i32 s20, 24
	s_movk_i32 s4, 0x3000
	s_cselect_b32 s28, s4, 0x6000
	s_cmp_lt_i32 s20, 16
	s_cselect_b64 vcc, -1, 0
	v_or_b32_e32 v210, s5, v221
	s_and_b64 s[4:5], vcc, exec
	s_cselect_b32 s20, 0, s28
	s_cselect_b32 s4, s6, s21
	s_cselect_b32 s5, s7, s24
	s_lshl_b32 s20, s20, 2
	s_add_u32 s20, s25, s20
	s_addc_u32 s21, s27, 0
	v_lshlrev_b32_e32 v0, 11, v210
	s_add_u32 s20, s20, 0x580000
	v_add_u32_e32 v130, 0x7f800000, v0
	s_addc_u32 s21, s21, 0
	v_ashrrev_i32_e32 v209, 31, v208
	v_cndmask_b32_e32 v0, v130, v0, vcc
	v_lshl_add_u64 v[130:131], v[208:209], 2, s[20:21]
	s_movk_i32 s24, 0x4000
	v_add_lshl_u32 v146, v0, v208, 1
	v_add_co_u32_e32 v132, vcc, s24, v130
	s_barrier
	global_load_dwordx4 v[202:205], v146, s[4:5]
	v_addc_co_u32_e32 v133, vcc, 0, v131, vcc
	global_load_dwordx4 v[142:145], v[132:133], off
	s_mov_b64 s[24:25], 0x4000
	v_lshl_add_u64 v[134:135], v[130:131], 0, s[24:25]
	global_load_dwordx4 v[138:141], v[134:135], off offset:16
	global_load_dwordx4 v[214:217], v146, s[4:5] offset:256
	global_load_dwordx4 v[130:133], v[134:135], off offset:528
	s_nop 0
	global_load_dwordx4 v[134:137], v[134:135], off offset:512
	v_add_u32_e32 v147, 0x10000, v146
	v_or_b32_e32 v148, 0x100, v147
	global_load_dwordx4 v[198:201], v147, s[4:5]
	global_load_dwordx4 v[194:197], v148, s[4:5]
	v_add_u32_e32 v147, 0x20000, v146
	v_add_u32_e32 v146, 0x30000, v146
	v_add_u32_e32 v0, 0x40000, v0
	v_or_b32_e32 v148, 0x100, v147
	global_load_dwordx4 v[190:193], v147, s[4:5]
	global_load_dwordx4 v[186:189], v148, s[4:5]
	v_or_b32_e32 v147, 0x100, v146
	global_load_dwordx4 v[178:181], v146, s[4:5]
	global_load_dwordx4 v[174:177], v147, s[4:5]
	v_add_lshl_u32 v146, v0, v208, 1
	v_or_b32_e32 v147, 0x100, v146
	global_load_dwordx4 v[182:185], v146, s[4:5]
	global_load_dwordx4 v[170:173], v147, s[4:5]
	v_or_b32_e32 v146, 0x8000, v0
	v_add_lshl_u32 v146, v146, v208, 1
	v_or_b32_e32 v147, 0x100, v146
	global_load_dwordx4 v[166:169], v146, s[4:5]
	global_load_dwordx4 v[162:165], v147, s[4:5]
	v_or_b32_e32 v146, 0x10000, v0
	v_or_b32_e32 v0, 0x18000, v0
	v_add_lshl_u32 v146, v146, v208, 1
	v_add_lshl_u32 v0, v0, v208, 1
	v_or_b32_e32 v147, 0x100, v146
	global_load_dwordx4 v[158:161], v146, s[4:5]
	global_load_dwordx4 v[154:157], v147, s[4:5]
	v_or_b32_e32 v146, 0x100, v0
	global_load_dwordx4 v[150:153], v0, s[4:5]
	s_nop 0
	global_load_dwordx4 v[146:149], v146, s[4:5]
	v_and_b32_e32 v226, 63, v212
	s_lshl_b32 s4, s33, 2
	s_add_i32 s4, s4, 0
	v_cmp_gt_u32_e32 vcc, 16, v226
	v_lshl_add_u32 v211, v211, 4, s4
	s_waitcnt vmcnt(0)
	v_lshlrev_b32_e32 v206, 16, v202
	v_and_b32_e32 v207, 0xffff0000, v202
	v_lshlrev_b32_e32 v202, 16, v203
	v_and_b32_e32 v203, 0xffff0000, v203
	v_lshlrev_b32_e32 v218, 16, v204
	v_and_b32_e32 v219, 0xffff0000, v204
	v_lshlrev_b32_e32 v204, 16, v205
	v_and_b32_e32 v205, 0xffff0000, v205
	v_pk_fma_f32 v[128:129], v[128:129], v[144:145], v[202:203]
	v_pk_fma_f32 v[126:127], v[126:127], v[142:143], v[206:207]
	v_pk_fma_f32 v[124:125], v[124:125], v[140:141], v[204:205]
	v_pk_fma_f32 v[122:123], v[122:123], v[138:139], v[218:219]
	v_mul_f32_e32 v0, v127, v127
	v_mul_f32_e32 v202, v129, v129
	v_mul_f32_e32 v203, v123, v123
	v_mul_f32_e32 v204, v125, v125
	v_fmac_f32_e32 v0, v126, v126
	v_fmac_f32_e32 v202, v128, v128
	v_fmac_f32_e32 v203, v122, v122
	v_fmac_f32_e32 v204, v124, v124
	v_add_f32_e32 v0, v0, v202
	v_add_f32_e32 v202, v203, v204
	v_add_f32_e32 v0, v0, v202
	v_lshlrev_b32_e32 v202, 16, v214
	v_and_b32_e32 v203, 0xffff0000, v214
	v_lshlrev_b32_e32 v204, 16, v215
	v_and_b32_e32 v205, 0xffff0000, v215
	v_pk_fma_f32 v[120:121], v[120:121], v[136:137], v[204:205]
	v_pk_fma_f32 v[118:119], v[118:119], v[134:135], v[202:203]
	v_lshlrev_b32_e32 v206, 16, v216
	v_and_b32_e32 v207, 0xffff0000, v216
	v_lshlrev_b32_e32 v214, 16, v217
	v_and_b32_e32 v215, 0xffff0000, v217
	v_mul_f32_e32 v202, v119, v119
	v_mul_f32_e32 v203, v121, v121
	v_pk_fma_f32 v[116:117], v[116:117], v[132:133], v[214:215]
	v_pk_fma_f32 v[114:115], v[114:115], v[130:131], v[206:207]
	v_fmac_f32_e32 v202, v118, v118
	v_fmac_f32_e32 v203, v120, v120
	v_add_f32_e32 v202, v202, v203
	v_mul_f32_e32 v203, v115, v115
	v_mul_f32_e32 v204, v117, v117
	v_fmac_f32_e32 v203, v114, v114
	v_fmac_f32_e32 v204, v116, v116
	v_add_f32_e32 v203, v203, v204
	v_add_f32_e32 v202, v202, v203
	v_lshlrev_b32_e32 v203, 2, v226
	v_add_f32_e32 v202, v0, v202
	v_xor_b32_e32 v0, 64, v203
	v_mov_b32_e32 v204, v202
	s_nop 1
	v_permlane16_swap_b32 v204, v202
	s_nop 1
	v_xor_b32_e32 v213, 0x80, v203
	s_waitcnt lgkmcnt(0)
	v_add_f32_e32 v214, v202, v204
	v_mov_b32_e32 v215, v214
	s_nop 1
	v_permlane32_swap_b32 v215, v214
	s_nop 1
	s_and_saveexec_b64 s[4:5], vcc
	s_cbranch_execz .LBB0_896
	s_waitcnt lgkmcnt(0)
	v_add_f32_e32 v202, v214, v215
	ds_write_b32 v211, v202
.LBB0_896:
	s_or_b64 exec, exec, s[4:5]
	v_lshlrev_b32_e32 v202, 16, v198
	v_and_b32_e32 v203, 0xffff0000, v198
	v_lshlrev_b32_e32 v198, 16, v199
	v_and_b32_e32 v199, 0xffff0000, v199
	v_pk_fma_f32 v[112:113], v[112:113], v[144:145], v[198:199]
	v_pk_fma_f32 v[110:111], v[110:111], v[142:143], v[202:203]
	v_lshlrev_b32_e32 v204, 16, v200
	v_and_b32_e32 v205, 0xffff0000, v200
	v_lshlrev_b32_e32 v200, 16, v201
	v_and_b32_e32 v201, 0xffff0000, v201
	v_mul_f32_e32 v198, v111, v111
	v_mul_f32_e32 v199, v113, v113
	v_pk_fma_f32 v[108:109], v[108:109], v[140:141], v[200:201]
	v_pk_fma_f32 v[106:107], v[106:107], v[138:139], v[204:205]
	v_fmac_f32_e32 v198, v110, v110
	v_fmac_f32_e32 v199, v112, v112
	v_add_f32_e32 v198, v198, v199
	v_mul_f32_e32 v199, v107, v107
	v_mul_f32_e32 v200, v109, v109
	v_fmac_f32_e32 v199, v106, v106
	v_fmac_f32_e32 v200, v108, v108
	v_add_f32_e32 v199, v199, v200
	v_add_f32_e32 v202, v198, v199
	v_lshlrev_b32_e32 v198, 16, v194
	v_and_b32_e32 v199, 0xffff0000, v194
	v_lshlrev_b32_e32 v194, 16, v195
	v_and_b32_e32 v195, 0xffff0000, v195
	v_pk_fma_f32 v[104:105], v[104:105], v[136:137], v[194:195]
	v_pk_fma_f32 v[102:103], v[102:103], v[134:135], v[198:199]
	v_lshlrev_b32_e32 v200, 16, v196
	v_and_b32_e32 v201, 0xffff0000, v196
	v_lshlrev_b32_e32 v196, 16, v197
	v_and_b32_e32 v197, 0xffff0000, v197
	v_mul_f32_e32 v194, v103, v103
	v_mul_f32_e32 v195, v105, v105
	v_pk_fma_f32 v[96:97], v[96:97], v[132:133], v[196:197]
	v_pk_fma_f32 v[94:95], v[94:95], v[130:131], v[200:201]
	v_fmac_f32_e32 v194, v102, v102
	v_fmac_f32_e32 v195, v104, v104
	v_add_f32_e32 v194, v194, v195
	v_mul_f32_e32 v195, v95, v95
	v_mul_f32_e32 v196, v97, v97
	v_fmac_f32_e32 v195, v94, v94
	v_fmac_f32_e32 v196, v96, v96
	v_add_f32_e32 v195, v195, v196
	v_add_f32_e32 v194, v194, v195
	v_add_f32_e32 v194, v202, v194
	v_mov_b32_e32 v195, v194
	s_nop 1
	v_permlane16_swap_b32 v195, v194
	s_nop 1
	s_waitcnt lgkmcnt(0)
	v_add_f32_e32 v194, v194, v195
	v_mov_b32_e32 v195, v194
	s_nop 1
	v_permlane32_swap_b32 v195, v194
	s_nop 1
	s_and_saveexec_b64 s[4:5], vcc
	s_cbranch_execz .LBB0_898
	s_waitcnt lgkmcnt(0)
	v_add_f32_e32 v194, v194, v195
	ds_write_b32 v211, v194 offset:256
.LBB0_898:
	s_or_b64 exec, exec, s[4:5]
	v_lshlrev_b32_e32 v194, 16, v190
	s_waitcnt lgkmcnt(0)
	v_and_b32_e32 v195, 0xffff0000, v190
	v_lshlrev_b32_e32 v190, 16, v191
	v_and_b32_e32 v191, 0xffff0000, v191
	v_pk_fma_f32 v[100:101], v[100:101], v[144:145], v[190:191]
	v_pk_fma_f32 v[98:99], v[98:99], v[142:143], v[194:195]
	v_lshlrev_b32_e32 v196, 16, v192
	v_and_b32_e32 v197, 0xffff0000, v192
	v_lshlrev_b32_e32 v192, 16, v193
	v_and_b32_e32 v193, 0xffff0000, v193
	v_mul_f32_e32 v190, v99, v99
	v_mul_f32_e32 v191, v101, v101
	v_pk_fma_f32 v[92:93], v[92:93], v[140:141], v[192:193]
	v_pk_fma_f32 v[90:91], v[90:91], v[138:139], v[196:197]
	v_fmac_f32_e32 v190, v98, v98
	v_fmac_f32_e32 v191, v100, v100
	v_add_f32_e32 v190, v190, v191
	v_mul_f32_e32 v191, v91, v91
	v_mul_f32_e32 v192, v93, v93
	v_fmac_f32_e32 v191, v90, v90
	v_fmac_f32_e32 v192, v92, v92
	v_add_f32_e32 v191, v191, v192
	v_add_f32_e32 v194, v190, v191
	v_lshlrev_b32_e32 v190, 16, v186
	v_and_b32_e32 v191, 0xffff0000, v186
	v_lshlrev_b32_e32 v186, 16, v187
	v_and_b32_e32 v187, 0xffff0000, v187
	v_pk_fma_f32 v[88:89], v[88:89], v[136:137], v[186:187]
	v_pk_fma_f32 v[86:87], v[86:87], v[134:135], v[190:191]
	v_lshlrev_b32_e32 v192, 16, v188
	v_and_b32_e32 v193, 0xffff0000, v188
	v_lshlrev_b32_e32 v188, 16, v189
	v_and_b32_e32 v189, 0xffff0000, v189
	v_mul_f32_e32 v186, v87, v87
	v_mul_f32_e32 v187, v89, v89
	v_pk_fma_f32 v[80:81], v[80:81], v[132:133], v[188:189]
	v_pk_fma_f32 v[78:79], v[78:79], v[130:131], v[192:193]
	v_fmac_f32_e32 v186, v86, v86
	v_fmac_f32_e32 v187, v88, v88
	v_add_f32_e32 v186, v186, v187
	v_mul_f32_e32 v187, v79, v79
	v_mul_f32_e32 v188, v81, v81
	v_fmac_f32_e32 v187, v78, v78
	v_fmac_f32_e32 v188, v80, v80
	v_add_f32_e32 v187, v187, v188
	v_add_f32_e32 v186, v186, v187
	v_add_f32_e32 v186, v194, v186
	v_mov_b32_e32 v187, v186
	s_nop 1
	v_permlane16_swap_b32 v187, v186
	s_nop 1
	s_waitcnt lgkmcnt(0)
	v_add_f32_e32 v186, v186, v187
	v_mov_b32_e32 v187, v186
	s_nop 1
	v_permlane32_swap_b32 v187, v186
	s_nop 1
	s_and_saveexec_b64 s[4:5], vcc
	s_cbranch_execz .LBB0_900
	s_waitcnt lgkmcnt(0)
	v_add_f32_e32 v186, v186, v187
	ds_write_b32 v211, v186 offset:512
.LBB0_900:
	s_or_b64 exec, exec, s[4:5]
	v_lshlrev_b32_e32 v186, 16, v178
	s_waitcnt lgkmcnt(0)
	v_and_b32_e32 v187, 0xffff0000, v178
	v_lshlrev_b32_e32 v178, 16, v179
	v_and_b32_e32 v179, 0xffff0000, v179
	v_pk_fma_f32 v[84:85], v[84:85], v[144:145], v[178:179]
	v_pk_fma_f32 v[82:83], v[82:83], v[142:143], v[186:187]
	v_lshlrev_b32_e32 v188, 16, v180
	v_and_b32_e32 v189, 0xffff0000, v180
	v_lshlrev_b32_e32 v180, 16, v181
	v_and_b32_e32 v181, 0xffff0000, v181
	v_mul_f32_e32 v178, v83, v83
	v_mul_f32_e32 v179, v85, v85
	v_pk_fma_f32 v[76:77], v[76:77], v[140:141], v[180:181]
	v_pk_fma_f32 v[74:75], v[74:75], v[138:139], v[188:189]
	v_fmac_f32_e32 v178, v82, v82
	v_fmac_f32_e32 v179, v84, v84
	v_add_f32_e32 v178, v178, v179
	v_mul_f32_e32 v179, v75, v75
	v_mul_f32_e32 v180, v77, v77
	v_fmac_f32_e32 v179, v74, v74
	v_fmac_f32_e32 v180, v76, v76
	v_add_f32_e32 v179, v179, v180
	v_add_f32_e32 v186, v178, v179
	v_lshlrev_b32_e32 v178, 16, v174
	v_and_b32_e32 v179, 0xffff0000, v174
	v_lshlrev_b32_e32 v174, 16, v175
	v_and_b32_e32 v175, 0xffff0000, v175
	v_pk_fma_f32 v[72:73], v[72:73], v[136:137], v[174:175]
	v_pk_fma_f32 v[70:71], v[70:71], v[134:135], v[178:179]
	v_lshlrev_b32_e32 v180, 16, v176
	v_and_b32_e32 v181, 0xffff0000, v176
	v_lshlrev_b32_e32 v176, 16, v177
	v_and_b32_e32 v177, 0xffff0000, v177
	v_mul_f32_e32 v174, v71, v71
	v_mul_f32_e32 v175, v73, v73
	v_pk_fma_f32 v[68:69], v[68:69], v[132:133], v[176:177]
	v_pk_fma_f32 v[66:67], v[66:67], v[130:131], v[180:181]
	v_fmac_f32_e32 v174, v70, v70
	v_fmac_f32_e32 v175, v72, v72
	v_add_f32_e32 v174, v174, v175
	v_mul_f32_e32 v175, v67, v67
	v_mul_f32_e32 v176, v69, v69
	v_fmac_f32_e32 v175, v66, v66
	v_fmac_f32_e32 v176, v68, v68
	v_add_f32_e32 v175, v175, v176
	v_add_f32_e32 v174, v174, v175
	v_add_f32_e32 v174, v186, v174
	v_mov_b32_e32 v175, v174
	s_nop 1
	v_permlane16_swap_b32 v175, v174
	s_nop 1
	s_waitcnt lgkmcnt(0)
	v_add_f32_e32 v174, v174, v175
	v_mov_b32_e32 v175, v174
	s_nop 1
	v_permlane32_swap_b32 v175, v174
	s_nop 1
	s_and_saveexec_b64 s[4:5], vcc
	s_cbranch_execz .LBB0_902
	s_waitcnt lgkmcnt(0)
	v_add_f32_e32 v174, v174, v175
	ds_write_b32 v211, v174 offset:768
.LBB0_902:
	s_or_b64 exec, exec, s[4:5]
	v_lshlrev_b32_e32 v176, 16, v182
	v_and_b32_e32 v177, 0xffff0000, v182
	v_lshlrev_b32_e32 v174, 16, v183
	s_waitcnt lgkmcnt(0)
	v_and_b32_e32 v175, 0xffff0000, v183
	v_lshlrev_b32_e32 v180, 16, v184
	v_and_b32_e32 v181, 0xffff0000, v184
	v_pk_fma_f32 v[174:175], v[64:65], v[144:145], v[174:175]
	v_pk_fma_f32 v[176:177], v[62:63], v[142:143], v[176:177]
	v_lshlrev_b32_e32 v178, 16, v185
	v_and_b32_e32 v179, 0xffff0000, v185
	v_pk_fma_f32 v[180:181], v[58:59], v[138:139], v[180:181]
	v_mul_f32_e32 v58, v177, v177
	v_mul_f32_e32 v59, v175, v175
	v_pk_fma_f32 v[178:179], v[60:61], v[140:141], v[178:179]
	v_fmac_f32_e32 v58, v176, v176
	v_fmac_f32_e32 v59, v174, v174
	v_add_f32_e32 v58, v58, v59
	v_mul_f32_e32 v59, v181, v181
	v_mul_f32_e32 v60, v179, v179
	v_fmac_f32_e32 v59, v180, v180
	v_fmac_f32_e32 v60, v178, v178
	v_add_f32_e32 v59, v59, v60
	v_add_f32_e32 v182, v58, v59
	v_lshlrev_b32_e32 v58, 16, v170
	v_and_b32_e32 v59, 0xffff0000, v170
	v_lshlrev_b32_e32 v60, 16, v171
	v_and_b32_e32 v61, 0xffff0000, v171
	v_lshlrev_b32_e32 v62, 16, v172
	v_and_b32_e32 v63, 0xffff0000, v172
	v_pk_fma_f32 v[56:57], v[56:57], v[136:137], v[60:61]
	v_pk_fma_f32 v[54:55], v[54:55], v[134:135], v[58:59]
	v_lshlrev_b32_e32 v64, 16, v173
	v_and_b32_e32 v65, 0xffff0000, v173
	v_pk_fma_f32 v[60:61], v[46:47], v[130:131], v[62:63]
	v_mul_f32_e32 v46, v55, v55
	v_mul_f32_e32 v47, v57, v57
	v_pk_fma_f32 v[58:59], v[48:49], v[132:133], v[64:65]
	v_fmac_f32_e32 v46, v54, v54
	v_fmac_f32_e32 v47, v56, v56
	v_add_f32_e32 v46, v46, v47
	v_mul_f32_e32 v47, v61, v61
	v_mul_f32_e32 v48, v59, v59
	v_fmac_f32_e32 v47, v60, v60
	v_fmac_f32_e32 v48, v58, v58
	v_add_f32_e32 v47, v47, v48
	v_add_f32_e32 v46, v46, v47
	v_add_f32_e32 v46, v182, v46
	v_mov_b32_e32 v47, v46
	s_nop 1
	v_permlane16_swap_b32 v47, v46
	s_nop 1
	s_waitcnt lgkmcnt(0)
	v_add_f32_e32 v46, v46, v47
	v_mov_b32_e32 v47, v46
	s_nop 1
	v_permlane32_swap_b32 v47, v46
	s_nop 1
	s_and_saveexec_b64 s[4:5], vcc
	s_cbranch_execz .LBB0_904
	s_waitcnt lgkmcnt(0)
	v_add_f32_e32 v46, v46, v47
	ds_write_b32 v211, v46 offset:2048
.LBB0_904:
	s_or_b64 exec, exec, s[4:5]
	v_lshlrev_b32_e32 v46, 16, v166
	s_waitcnt lgkmcnt(0)
	v_and_b32_e32 v47, 0xffff0000, v166
	v_lshlrev_b32_e32 v48, 16, v167
	v_and_b32_e32 v49, 0xffff0000, v167
	v_lshlrev_b32_e32 v62, 16, v168
	v_and_b32_e32 v63, 0xffff0000, v168
	v_pk_fma_f32 v[166:167], v[52:53], v[144:145], v[48:49]
	v_pk_fma_f32 v[170:171], v[50:51], v[142:143], v[46:47]
	v_lshlrev_b32_e32 v64, 16, v169
	v_and_b32_e32 v65, 0xffff0000, v169
	v_pk_fma_f32 v[172:173], v[42:43], v[138:139], v[62:63]
	v_mul_f32_e32 v42, v171, v171
	v_mul_f32_e32 v43, v167, v167
	v_pk_fma_f32 v[168:169], v[44:45], v[140:141], v[64:65]
	v_fmac_f32_e32 v42, v170, v170
	v_fmac_f32_e32 v43, v166, v166
	v_add_f32_e32 v42, v42, v43
	v_mul_f32_e32 v43, v173, v173
	v_mul_f32_e32 v44, v169, v169
	v_fmac_f32_e32 v43, v172, v172
	v_fmac_f32_e32 v44, v168, v168
	v_add_f32_e32 v43, v43, v44
	v_add_f32_e32 v182, v42, v43
	v_lshlrev_b32_e32 v42, 16, v162
	v_and_b32_e32 v43, 0xffff0000, v162
	v_lshlrev_b32_e32 v44, 16, v163
	v_and_b32_e32 v45, 0xffff0000, v163
	v_lshlrev_b32_e32 v46, 16, v164
	v_and_b32_e32 v47, 0xffff0000, v164
	v_pk_fma_f32 v[50:51], v[40:41], v[136:137], v[44:45]
	v_pk_fma_f32 v[62:63], v[38:39], v[134:135], v[42:43]
	v_lshlrev_b32_e32 v48, 16, v165
	v_and_b32_e32 v49, 0xffff0000, v165
	v_pk_fma_f32 v[64:65], v[30:31], v[130:131], v[46:47]
	v_mul_f32_e32 v30, v63, v63
	v_mul_f32_e32 v31, v51, v51
	v_pk_fma_f32 v[52:53], v[32:33], v[132:133], v[48:49]
	v_fmac_f32_e32 v30, v62, v62
	v_fmac_f32_e32 v31, v50, v50
	v_add_f32_e32 v30, v30, v31
	v_mul_f32_e32 v31, v65, v65
	v_mul_f32_e32 v32, v53, v53
	v_fmac_f32_e32 v31, v64, v64
	v_fmac_f32_e32 v32, v52, v52
	v_add_f32_e32 v31, v31, v32
	v_add_f32_e32 v30, v30, v31
	v_add_f32_e32 v30, v182, v30
	v_mov_b32_e32 v31, v30
	s_nop 1
	v_permlane16_swap_b32 v31, v30
	s_nop 1
	s_waitcnt lgkmcnt(0)
	v_add_f32_e32 v30, v30, v31
	v_mov_b32_e32 v31, v30
	s_nop 1
	v_permlane32_swap_b32 v31, v30
	s_nop 1
	s_and_saveexec_b64 s[4:5], vcc
	s_cbranch_execz .LBB0_906
	s_waitcnt lgkmcnt(0)
	v_add_f32_e32 v30, v30, v31
	ds_write_b32 v211, v30 offset:2304
.LBB0_906:
	s_or_b64 exec, exec, s[4:5]
	v_lshlrev_b32_e32 v30, 16, v158
	s_waitcnt lgkmcnt(0)
	v_and_b32_e32 v31, 0xffff0000, v158
	v_lshlrev_b32_e32 v32, 16, v159
	v_and_b32_e32 v33, 0xffff0000, v159
	v_lshlrev_b32_e32 v38, 16, v160
	v_and_b32_e32 v39, 0xffff0000, v160
	v_pk_fma_f32 v[162:163], v[36:37], v[144:145], v[32:33]
	v_pk_fma_f32 v[164:165], v[34:35], v[142:143], v[30:31]
	v_lshlrev_b32_e32 v40, 16, v161
	v_and_b32_e32 v41, 0xffff0000, v161
	v_pk_fma_f32 v[184:185], v[26:27], v[138:139], v[38:39]
	v_mul_f32_e32 v26, v165, v165
	v_mul_f32_e32 v27, v163, v163
	v_pk_fma_f32 v[182:183], v[28:29], v[140:141], v[40:41]
	v_fmac_f32_e32 v26, v164, v164
	v_fmac_f32_e32 v27, v162, v162
	v_add_f32_e32 v26, v26, v27
	v_mul_f32_e32 v27, v185, v185
	v_mul_f32_e32 v28, v183, v183
	v_fmac_f32_e32 v27, v184, v184
	v_fmac_f32_e32 v28, v182, v182
	v_add_f32_e32 v27, v27, v28
	v_add_f32_e32 v34, v26, v27
	v_lshlrev_b32_e32 v26, 16, v154
	v_and_b32_e32 v27, 0xffff0000, v154
	v_lshlrev_b32_e32 v28, 16, v155
	v_and_b32_e32 v29, 0xffff0000, v155
	v_lshlrev_b32_e32 v30, 16, v156
	v_and_b32_e32 v31, 0xffff0000, v156
	v_lshlrev_b32_e32 v32, 16, v157
	v_and_b32_e32 v33, 0xffff0000, v157
	v_pk_fma_f32 v[154:155], v[24:25], v[136:137], v[28:29]
	v_pk_fma_f32 v[156:157], v[22:23], v[134:135], v[26:27]
	v_pk_fma_f32 v[160:161], v[14:15], v[130:131], v[30:31]
	v_mul_f32_e32 v14, v157, v157
	v_mul_f32_e32 v15, v155, v155
	v_pk_fma_f32 v[158:159], v[16:17], v[132:133], v[32:33]
	v_fmac_f32_e32 v14, v156, v156
	v_fmac_f32_e32 v15, v154, v154
	v_add_f32_e32 v14, v14, v15
	v_mul_f32_e32 v15, v161, v161
	v_mul_f32_e32 v16, v159, v159
	v_fmac_f32_e32 v15, v160, v160
	v_fmac_f32_e32 v16, v158, v158
	v_add_f32_e32 v15, v15, v16
	v_add_f32_e32 v14, v14, v15
	v_add_f32_e32 v14, v34, v14
	v_mov_b32_e32 v15, v14
	s_nop 1
	v_permlane16_swap_b32 v15, v14
	s_nop 1
	s_waitcnt lgkmcnt(0)
	v_add_f32_e32 v14, v14, v15
	v_mov_b32_e32 v15, v14
	s_nop 1
	v_permlane32_swap_b32 v15, v14
	s_nop 1
	s_and_saveexec_b64 s[4:5], vcc
	s_cbranch_execz .LBB0_908
	s_waitcnt lgkmcnt(0)
	v_add_f32_e32 v14, v14, v15
	ds_write_b32 v211, v14 offset:2560
.LBB0_908:
	s_or_b64 exec, exec, s[4:5]
	v_lshlrev_b32_e32 v14, 16, v150
	s_waitcnt lgkmcnt(0)
	v_and_b32_e32 v15, 0xffff0000, v150
	v_lshlrev_b32_e32 v16, 16, v151
	v_and_b32_e32 v17, 0xffff0000, v151
	v_lshlrev_b32_e32 v22, 16, v152
	v_and_b32_e32 v23, 0xffff0000, v152
	v_pk_fma_f32 v[144:145], v[20:21], v[144:145], v[16:17]
	v_pk_fma_f32 v[142:143], v[18:19], v[142:143], v[14:15]
	v_lshlrev_b32_e32 v24, 16, v153
	v_and_b32_e32 v25, 0xffff0000, v153
	v_pk_fma_f32 v[138:139], v[10:11], v[138:139], v[22:23]
	v_mul_f32_e32 v10, v143, v143
	v_mul_f32_e32 v11, v145, v145
	v_pk_fma_f32 v[140:141], v[12:13], v[140:141], v[24:25]
	v_fmac_f32_e32 v10, v142, v142
	v_fmac_f32_e32 v11, v144, v144
	v_add_f32_e32 v10, v10, v11
	v_mul_f32_e32 v11, v139, v139
	v_mul_f32_e32 v12, v141, v141
	v_fmac_f32_e32 v11, v138, v138
	v_fmac_f32_e32 v12, v140, v140
	v_add_f32_e32 v11, v11, v12
	v_add_f32_e32 v18, v10, v11
	v_lshlrev_b32_e32 v10, 16, v146
	v_and_b32_e32 v11, 0xffff0000, v146
	v_lshlrev_b32_e32 v12, 16, v147
	v_and_b32_e32 v13, 0xffff0000, v147
	v_lshlrev_b32_e32 v14, 16, v148
	v_and_b32_e32 v15, 0xffff0000, v148
	v_pk_fma_f32 v[136:137], v[8:9], v[136:137], v[12:13]
	v_pk_fma_f32 v[134:135], v[6:7], v[134:135], v[10:11]
	v_lshlrev_b32_e32 v16, 16, v149
	v_and_b32_e32 v17, 0xffff0000, v149
	v_pk_fma_f32 v[130:131], v[2:3], v[130:131], v[14:15]
	v_mul_f32_e32 v2, v135, v135
	v_mul_f32_e32 v3, v137, v137
	v_pk_fma_f32 v[132:133], v[4:5], v[132:133], v[16:17]
	v_fmac_f32_e32 v2, v134, v134
	v_fmac_f32_e32 v3, v136, v136
	v_add_f32_e32 v2, v2, v3
	v_mul_f32_e32 v3, v131, v131
	v_mul_f32_e32 v4, v133, v133
	v_fmac_f32_e32 v3, v130, v130
	v_fmac_f32_e32 v4, v132, v132
	v_add_f32_e32 v3, v3, v4
	v_add_f32_e32 v2, v2, v3
	v_add_f32_e32 v2, v18, v2
	v_mov_b32_e32 v0, v2
	s_nop 1
	v_permlane16_swap_b32 v0, v2
	s_nop 1
	s_waitcnt lgkmcnt(0)
	v_add_f32_e32 v0, v2, v0
	v_mov_b32_e32 v2, v0
	s_nop 1
	v_permlane32_swap_b32 v2, v0
	s_nop 1
	s_and_saveexec_b64 s[4:5], vcc
	s_cbranch_execz .LBB0_910
	s_waitcnt lgkmcnt(0)
	v_add_f32_e32 v0, v0, v2
	ds_write_b32 v211, v0 offset:2816

.LBB0_954:
	s_lshl_b32 s4, s33, 5
	s_lshl_b32 s26, s18, 8
	s_lshl_b32 s6, s16, 8
	v_lshrrev_b32_e32 v0, 1, v220
	s_add_i32 s5, s26, s86
	s_or_b32 s4, s6, s4
	v_and_or_b32 v146, v0, 24, s4
	s_cmp_lt_i32 s18, 24
	s_movk_i32 s4, 0x3000
	s_cselect_b32 s19, s4, 0x6000
	s_cmp_lt_i32 s18, 16
	v_or_b32_e32 v150, s5, v221
	s_cselect_b64 s[4:5], -1, 0
	s_and_b64 s[6:7], s[4:5], exec
	s_cselect_b32 s6, 0, s19
	s_cselect_b32 s19, s21, s25
	s_cselect_b32 s18, s20, s24
	s_lshl_b32 s6, s6, 2
	s_add_u32 s6, s10, s6
	s_addc_u32 s7, s11, 0
	v_add_u32_e32 v0, 0xfffff000, v150
	s_add_u32 s6, s6, 0x580000
	v_ashrrev_i32_e32 v147, 31, v146
	v_cndmask_b32_e64 v114, v0, v150, s[4:5]
	s_addc_u32 s7, s7, 0
	v_lshlrev_b64 v[148:149], 2, v[146:147]
	v_lshl_add_u64 v[116:117], s[6:7], 0, v[148:149]
	s_movk_i32 s20, 0x4000
	v_ashrrev_i32_e32 v115, 31, v114
	v_add_co_u32_e32 v118, vcc, s20, v116
	v_lshlrev_b64 v[114:115], 13, v[114:115]
	s_nop 0
	v_addc_co_u32_e32 v119, vcc, 0, v117, vcc
	v_lshl_add_u64 v[114:115], s[18:19], 0, v[114:115]
	s_barrier
	global_load_dwordx4 v[122:125], v[118:119], off
	v_lshl_add_u64 v[118:119], v[114:115], 0, v[148:149]
	global_load_dwordx4 v[152:155], v[118:119], off offset:16
	global_load_dwordx4 v[156:159], v[118:119], off
	s_mov_b64 s[20:21], 0x4000
	v_lshl_add_u64 v[120:121], v[116:117], 0, s[20:21]
	global_load_dwordx4 v[126:129], v[120:121], off offset:16
	global_load_dwordx4 v[114:117], v[120:121], off offset:512
	global_load_dwordx4 v[160:163], v[118:119], off offset:512
	global_load_dwordx4 v[164:167], v[118:119], off offset:528
	s_nop 0
	global_load_dwordx4 v[118:121], v[120:121], off offset:528
	v_and_b32_e32 v226, 63, v220
	v_lshlrev_b32_e32 v168, 2, v226
	v_xor_b32_e32 v0, 64, v168
	s_lshl_b32 s20, s33, 2
	s_add_i32 s20, s20, 0
	v_cmp_gt_u32_e32 vcc, 16, v226
	v_lshl_add_u32 v151, v151, 4, s20
	s_waitcnt vmcnt(0)
	v_pk_fma_f32 v[140:141], v[140:141], v[128:129], v[154:155]
	v_pk_fma_f32 v[144:145], v[144:145], v[124:125], v[158:159]
	v_pk_fma_f32 v[142:143], v[142:143], v[122:123], v[156:157]
	v_pk_fma_f32 v[138:139], v[138:139], v[126:127], v[152:153]
	v_pk_fma_f32 v[136:137], v[136:137], v[116:117], v[162:163]
	v_pk_fma_f32 v[134:135], v[134:135], v[114:115], v[160:161]
	v_mul_f32_e32 v152, v143, v143
	v_mul_f32_e32 v153, v145, v145
	v_mul_f32_e32 v154, v139, v139
	v_mul_f32_e32 v155, v141, v141
	v_pk_fma_f32 v[132:133], v[132:133], v[120:121], v[166:167]
	v_pk_fma_f32 v[130:131], v[130:131], v[118:119], v[164:165]
	v_mul_f32_e32 v156, v135, v135
	v_mul_f32_e32 v157, v137, v137
	v_fmac_f32_e32 v152, v142, v142
	v_fmac_f32_e32 v153, v144, v144
	v_fmac_f32_e32 v154, v138, v138
	v_fmac_f32_e32 v155, v140, v140
	v_mul_f32_e32 v158, v131, v131
	v_mul_f32_e32 v159, v133, v133
	v_fmac_f32_e32 v156, v134, v134
	v_fmac_f32_e32 v157, v136, v136
	v_add_f32_e32 v152, v152, v153
	v_add_f32_e32 v153, v154, v155
	v_fmac_f32_e32 v158, v130, v130
	v_fmac_f32_e32 v159, v132, v132
	v_add_f32_e32 v154, v156, v157
	v_add_f32_e32 v152, v152, v153
	v_add_f32_e32 v152, v152, v154
	v_add_f32_e32 v153, v158, v159
	v_add_f32_e32 v152, v152, v153
	v_mov_b32_e32 v153, v152
	s_nop 1
	v_permlane16_swap_b32 v153, v152
	s_nop 1
	v_xor_b32_e32 v161, 0x80, v168
	s_waitcnt lgkmcnt(0)
	v_add_f32_e32 v152, v152, v153
	v_mov_b32_e32 v153, v152
	s_nop 1
	v_permlane32_swap_b32 v153, v152
	s_nop 1
	s_and_saveexec_b64 s[20:21], vcc
	s_cbranch_execz .LBB0_956
	s_waitcnt lgkmcnt(0)
	v_add_f32_e32 v152, v152, v153
	ds_write_b32 v151, v152
.LBB0_956:
	s_or_b64 exec, exec, s[20:21]
	v_or_b32_e32 v160, 16, v150
	v_add_u32_e32 v152, 0xfffff010, v150
	v_cndmask_b32_e64 v152, v152, v160, s[4:5]
	s_waitcnt lgkmcnt(0)
	v_ashrrev_i32_e32 v153, 31, v152
	v_lshlrev_b64 v[152:153], 13, v[152:153]
	v_lshl_add_u64 v[152:153], s[18:19], 0, v[152:153]
	v_lshl_add_u64 v[166:167], v[146:147], 2, v[152:153]
	global_load_dwordx4 v[152:155], v[166:167], off
	global_load_dwordx4 v[156:159], v[166:167], off offset:16
	global_load_dwordx4 v[162:165], v[166:167], off offset:512
	s_nop 0
	global_load_dwordx4 v[166:169], v[166:167], off offset:528
	s_waitcnt vmcnt(3)
	v_pk_fma_f32 v[112:113], v[112:113], v[124:125], v[154:155]
	v_pk_fma_f32 v[110:111], v[110:111], v[122:123], v[152:153]
	s_waitcnt vmcnt(2)
	v_pk_fma_f32 v[108:109], v[108:109], v[128:129], v[158:159]
	v_pk_fma_f32 v[106:107], v[106:107], v[126:127], v[156:157]
	s_waitcnt vmcnt(1)
	v_pk_fma_f32 v[104:105], v[104:105], v[116:117], v[164:165]
	v_pk_fma_f32 v[102:103], v[102:103], v[114:115], v[162:163]
	v_mul_f32_e32 v152, v111, v111
	v_mul_f32_e32 v153, v113, v113
	v_mul_f32_e32 v154, v107, v107
	v_mul_f32_e32 v155, v109, v109
	s_waitcnt vmcnt(0)
	v_pk_fma_f32 v[100:101], v[100:101], v[120:121], v[168:169]
	v_pk_fma_f32 v[98:99], v[98:99], v[118:119], v[166:167]
	v_mul_f32_e32 v156, v103, v103
	v_mul_f32_e32 v157, v105, v105
	v_fmac_f32_e32 v152, v110, v110
	v_fmac_f32_e32 v153, v112, v112
	v_fmac_f32_e32 v154, v106, v106
	v_fmac_f32_e32 v155, v108, v108
	v_mul_f32_e32 v158, v99, v99
	v_mul_f32_e32 v159, v101, v101
	v_fmac_f32_e32 v156, v102, v102
	v_fmac_f32_e32 v157, v104, v104
	v_add_f32_e32 v152, v152, v153
	v_add_f32_e32 v153, v154, v155
	v_fmac_f32_e32 v158, v98, v98
	v_fmac_f32_e32 v159, v100, v100
	v_add_f32_e32 v154, v156, v157
	v_add_f32_e32 v152, v152, v153
	v_add_f32_e32 v152, v152, v154
	v_add_f32_e32 v153, v158, v159
	v_add_f32_e32 v152, v152, v153
	v_mov_b32_e32 v153, v152
	s_nop 1
	v_permlane16_swap_b32 v153, v152
	s_nop 1
	s_waitcnt lgkmcnt(0)
	v_add_f32_e32 v152, v152, v153
	v_mov_b32_e32 v153, v152
	s_nop 1
	v_permlane32_swap_b32 v153, v152
	s_nop 1
	s_and_saveexec_b64 s[20:21], vcc
	s_cbranch_execz .LBB0_958
	s_waitcnt lgkmcnt(0)
	v_add_f32_e32 v152, v152, v153
	ds_write_b32 v151, v152 offset:256
.LBB0_958:
	s_or_b64 exec, exec, s[20:21]
	v_or_b32_e32 v178, 32, v150
	v_add_u32_e32 v152, 0xfffff020, v150
	v_cndmask_b32_e64 v152, v152, v178, s[4:5]
	s_waitcnt lgkmcnt(0)
	v_ashrrev_i32_e32 v153, 31, v152
	v_lshlrev_b64 v[152:153], 13, v[152:153]
	v_lshl_add_u64 v[152:153], s[18:19], 0, v[152:153]
	v_lshl_add_u64 v[166:167], v[146:147], 2, v[152:153]
	global_load_dwordx4 v[152:155], v[166:167], off
	global_load_dwordx4 v[156:159], v[166:167], off offset:16
	global_load_dwordx4 v[162:165], v[166:167], off offset:512
	s_nop 0
	global_load_dwordx4 v[166:169], v[166:167], off offset:528
	s_waitcnt vmcnt(3)
	v_pk_fma_f32 v[96:97], v[96:97], v[124:125], v[154:155]
	v_pk_fma_f32 v[94:95], v[94:95], v[122:123], v[152:153]
	s_waitcnt vmcnt(2)
	v_pk_fma_f32 v[92:93], v[92:93], v[128:129], v[158:159]
	v_pk_fma_f32 v[90:91], v[90:91], v[126:127], v[156:157]
	s_waitcnt vmcnt(1)
	v_pk_fma_f32 v[88:89], v[88:89], v[116:117], v[164:165]
	v_pk_fma_f32 v[86:87], v[86:87], v[114:115], v[162:163]
	v_mul_f32_e32 v152, v95, v95
	v_mul_f32_e32 v153, v97, v97
	v_mul_f32_e32 v154, v91, v91
	v_mul_f32_e32 v155, v93, v93
	s_waitcnt vmcnt(0)
	v_pk_fma_f32 v[84:85], v[84:85], v[120:121], v[168:169]
	v_pk_fma_f32 v[82:83], v[82:83], v[118:119], v[166:167]
	v_mul_f32_e32 v156, v87, v87
	v_mul_f32_e32 v157, v89, v89
	v_fmac_f32_e32 v152, v94, v94
	v_fmac_f32_e32 v153, v96, v96
	v_fmac_f32_e32 v154, v90, v90
	v_fmac_f32_e32 v155, v92, v92
	v_mul_f32_e32 v158, v83, v83
	v_mul_f32_e32 v159, v85, v85
	v_fmac_f32_e32 v156, v86, v86
	v_fmac_f32_e32 v157, v88, v88
	v_add_f32_e32 v152, v152, v153
	v_add_f32_e32 v153, v154, v155
	v_fmac_f32_e32 v158, v82, v82
	v_fmac_f32_e32 v159, v84, v84
	v_add_f32_e32 v154, v156, v157
	v_add_f32_e32 v152, v152, v153
	v_add_f32_e32 v152, v152, v154
	v_add_f32_e32 v153, v158, v159
	v_add_f32_e32 v152, v152, v153
	v_mov_b32_e32 v153, v152
	s_nop 1
	v_permlane16_swap_b32 v153, v152
	s_nop 1
	s_waitcnt lgkmcnt(0)
	v_add_f32_e32 v152, v152, v153
	v_mov_b32_e32 v153, v152
	s_nop 1
	v_permlane32_swap_b32 v153, v152
	s_nop 1
	s_and_saveexec_b64 s[20:21], vcc
	s_cbranch_execz .LBB0_960
	s_waitcnt lgkmcnt(0)
	v_add_f32_e32 v152, v152, v153
	ds_write_b32 v151, v152 offset:512
.LBB0_960:
	s_or_b64 exec, exec, s[20:21]
	v_or_b32_e32 v188, 48, v150
	v_add_u32_e32 v152, 0xfffff030, v150
	v_cndmask_b32_e64 v152, v152, v188, s[4:5]
	s_waitcnt lgkmcnt(0)
	v_ashrrev_i32_e32 v153, 31, v152
	v_lshlrev_b64 v[152:153], 13, v[152:153]
	v_lshl_add_u64 v[152:153], s[18:19], 0, v[152:153]
	v_lshl_add_u64 v[166:167], v[146:147], 2, v[152:153]
	global_load_dwordx4 v[152:155], v[166:167], off
	global_load_dwordx4 v[156:159], v[166:167], off offset:16
	global_load_dwordx4 v[162:165], v[166:167], off offset:512
	s_nop 0
	global_load_dwordx4 v[166:169], v[166:167], off offset:528
	s_waitcnt vmcnt(3)
	v_pk_fma_f32 v[80:81], v[80:81], v[124:125], v[154:155]
	v_pk_fma_f32 v[78:79], v[78:79], v[122:123], v[152:153]
	s_waitcnt vmcnt(2)
	v_pk_fma_f32 v[76:77], v[76:77], v[128:129], v[158:159]
	v_pk_fma_f32 v[74:75], v[74:75], v[126:127], v[156:157]
	s_waitcnt vmcnt(1)
	v_pk_fma_f32 v[72:73], v[72:73], v[116:117], v[164:165]
	v_pk_fma_f32 v[70:71], v[70:71], v[114:115], v[162:163]
	v_mul_f32_e32 v152, v79, v79
	v_mul_f32_e32 v153, v81, v81
	v_mul_f32_e32 v154, v75, v75
	v_mul_f32_e32 v155, v77, v77
	s_waitcnt vmcnt(0)
	v_pk_fma_f32 v[68:69], v[68:69], v[120:121], v[168:169]
	v_pk_fma_f32 v[66:67], v[66:67], v[118:119], v[166:167]
	v_mul_f32_e32 v156, v71, v71
	v_mul_f32_e32 v157, v73, v73
	v_fmac_f32_e32 v152, v78, v78
	v_fmac_f32_e32 v153, v80, v80
	v_fmac_f32_e32 v154, v74, v74
	v_fmac_f32_e32 v155, v76, v76
	v_mul_f32_e32 v158, v67, v67
	v_mul_f32_e32 v159, v69, v69
	v_fmac_f32_e32 v156, v70, v70
	v_fmac_f32_e32 v157, v72, v72
	v_add_f32_e32 v152, v152, v153
	v_add_f32_e32 v153, v154, v155
	v_fmac_f32_e32 v158, v66, v66
	v_fmac_f32_e32 v159, v68, v68
	v_add_f32_e32 v154, v156, v157
	v_add_f32_e32 v152, v152, v153
	v_add_f32_e32 v152, v152, v154
	v_add_f32_e32 v153, v158, v159
	v_add_f32_e32 v152, v152, v153
	v_mov_b32_e32 v153, v152
	s_nop 1
	v_permlane16_swap_b32 v153, v152
	s_nop 1
	s_waitcnt lgkmcnt(0)
	v_add_f32_e32 v152, v152, v153
	v_mov_b32_e32 v153, v152
	s_nop 1
	v_permlane32_swap_b32 v153, v152
	s_nop 1
	s_and_saveexec_b64 s[20:21], vcc
	s_cbranch_execz .LBB0_962
	s_waitcnt lgkmcnt(0)
	v_add_f32_e32 v152, v152, v153
	ds_write_b32 v151, v152 offset:768
.LBB0_962:
	s_or_b64 exec, exec, s[20:21]
	v_add_u32_e32 v194, 0x80, v150
	v_add_u32_e32 v152, 0xfffff080, v150
	v_cndmask_b32_e64 v152, v152, v194, s[4:5]
	s_waitcnt lgkmcnt(0)
	v_ashrrev_i32_e32 v153, 31, v152
	v_lshlrev_b64 v[152:153], 13, v[152:153]
	v_lshl_add_u64 v[152:153], s[18:19], 0, v[152:153]
	v_lshl_add_u64 v[166:167], v[146:147], 2, v[152:153]
	global_load_dwordx4 v[152:155], v[166:167], off
	global_load_dwordx4 v[156:159], v[166:167], off offset:16
	global_load_dwordx4 v[162:165], v[166:167], off offset:512
	s_nop 0
	global_load_dwordx4 v[166:169], v[166:167], off offset:528
	s_waitcnt vmcnt(3)
	v_pk_fma_f32 v[64:65], v[64:65], v[124:125], v[154:155]
	v_pk_fma_f32 v[62:63], v[62:63], v[122:123], v[152:153]
	s_waitcnt vmcnt(2)
	v_pk_fma_f32 v[60:61], v[60:61], v[128:129], v[158:159]
	v_pk_fma_f32 v[58:59], v[58:59], v[126:127], v[156:157]
	s_waitcnt vmcnt(1)
	v_pk_fma_f32 v[56:57], v[56:57], v[116:117], v[164:165]
	v_pk_fma_f32 v[54:55], v[54:55], v[114:115], v[162:163]
	v_mul_f32_e32 v152, v63, v63
	v_mul_f32_e32 v153, v65, v65
	v_mul_f32_e32 v154, v59, v59
	v_mul_f32_e32 v155, v61, v61
	s_waitcnt vmcnt(0)
	v_pk_fma_f32 v[52:53], v[52:53], v[120:121], v[168:169]
	v_pk_fma_f32 v[50:51], v[50:51], v[118:119], v[166:167]
	v_mul_f32_e32 v156, v55, v55
	v_mul_f32_e32 v157, v57, v57
	v_fmac_f32_e32 v152, v62, v62
	v_fmac_f32_e32 v153, v64, v64
	v_fmac_f32_e32 v154, v58, v58
	v_fmac_f32_e32 v155, v60, v60
	v_mul_f32_e32 v158, v51, v51
	v_mul_f32_e32 v159, v53, v53
	v_fmac_f32_e32 v156, v54, v54
	v_fmac_f32_e32 v157, v56, v56
	v_add_f32_e32 v152, v152, v153
	v_add_f32_e32 v153, v154, v155
	v_fmac_f32_e32 v158, v50, v50
	v_fmac_f32_e32 v159, v52, v52
	v_add_f32_e32 v154, v156, v157
	v_add_f32_e32 v152, v152, v153
	v_add_f32_e32 v152, v152, v154
	v_add_f32_e32 v153, v158, v159
	v_add_f32_e32 v152, v152, v153
	v_mov_b32_e32 v153, v152
	s_nop 1
	v_permlane16_swap_b32 v153, v152
	s_nop 1
	s_waitcnt lgkmcnt(0)
	v_add_f32_e32 v152, v152, v153
	v_mov_b32_e32 v153, v152
	s_nop 1
	v_permlane32_swap_b32 v153, v152
	s_nop 1
	s_and_saveexec_b64 s[20:21], vcc
	s_cbranch_execz .LBB0_964
	s_waitcnt lgkmcnt(0)
	v_add_f32_e32 v152, v152, v153
	ds_write_b32 v151, v152 offset:2048
.LBB0_964:
	s_or_b64 exec, exec, s[20:21]
	v_add_u32_e32 v196, 0x90, v150
	v_add_u32_e32 v152, 0xfffff090, v150
	v_cndmask_b32_e64 v152, v152, v196, s[4:5]
	s_waitcnt lgkmcnt(0)
	v_ashrrev_i32_e32 v153, 31, v152
	v_lshlrev_b64 v[152:153], 13, v[152:153]
	v_lshl_add_u64 v[152:153], s[18:19], 0, v[152:153]
	v_lshl_add_u64 v[162:163], v[146:147], 2, v[152:153]
	global_load_dwordx4 v[152:155], v[162:163], off
	global_load_dwordx4 v[156:159], v[162:163], off offset:16
	global_load_dwordx4 v[170:173], v[162:163], off offset:512
	global_load_dwordx4 v[174:177], v[162:163], off offset:528
	s_waitcnt vmcnt(3)
	v_pk_fma_f32 v[166:167], v[48:49], v[124:125], v[154:155]
	v_pk_fma_f32 v[168:169], v[46:47], v[122:123], v[152:153]
	s_waitcnt vmcnt(2)
	v_pk_fma_f32 v[162:163], v[44:45], v[128:129], v[158:159]
	v_pk_fma_f32 v[164:165], v[42:43], v[126:127], v[156:157]
	s_waitcnt vmcnt(1)
	v_pk_fma_f32 v[152:153], v[40:41], v[116:117], v[172:173]
	v_pk_fma_f32 v[154:155], v[38:39], v[114:115], v[170:171]
	s_waitcnt vmcnt(0)
	v_pk_fma_f32 v[156:157], v[36:37], v[120:121], v[176:177]
	v_pk_fma_f32 v[158:159], v[34:35], v[118:119], v[174:175]
	v_mul_f32_e32 v34, v169, v169
	v_mul_f32_e32 v35, v167, v167
	v_mul_f32_e32 v36, v165, v165
	v_mul_f32_e32 v37, v163, v163
	v_mul_f32_e32 v38, v155, v155
	v_mul_f32_e32 v39, v153, v153
	v_fmac_f32_e32 v34, v168, v168
	v_fmac_f32_e32 v35, v166, v166
	v_fmac_f32_e32 v36, v164, v164
	v_fmac_f32_e32 v37, v162, v162
	v_mul_f32_e32 v40, v159, v159
	v_mul_f32_e32 v41, v157, v157
	v_fmac_f32_e32 v38, v154, v154
	v_fmac_f32_e32 v39, v152, v152
	v_add_f32_e32 v34, v34, v35
	v_add_f32_e32 v35, v36, v37
	v_fmac_f32_e32 v40, v158, v158
	v_fmac_f32_e32 v41, v156, v156
	v_add_f32_e32 v36, v38, v39
	v_add_f32_e32 v34, v34, v35
	v_add_f32_e32 v34, v34, v36
	v_add_f32_e32 v35, v40, v41
	v_add_f32_e32 v34, v34, v35
	v_mov_b32_e32 v35, v34
	s_nop 1
	v_permlane16_swap_b32 v35, v34
	s_nop 1
	s_waitcnt lgkmcnt(0)
	v_add_f32_e32 v34, v34, v35
	v_mov_b32_e32 v35, v34
	s_nop 1
	v_permlane32_swap_b32 v35, v34
	s_nop 1
	s_and_saveexec_b64 s[20:21], vcc
	s_cbranch_execz .LBB0_966
	s_waitcnt lgkmcnt(0)
	v_add_f32_e32 v34, v34, v35
	ds_write_b32 v151, v34 offset:2304
.LBB0_966:
	s_or_b64 exec, exec, s[20:21]
	v_add_u32_e32 v34, 0xa0, v150
	s_waitcnt lgkmcnt(0)
	v_add_u32_e32 v35, 0xfffff0a0, v150
	v_cndmask_b32_e64 v36, v35, v34, s[4:5]
	v_ashrrev_i32_e32 v37, 31, v36
	v_lshlrev_b64 v[36:37], 13, v[36:37]
	v_lshl_add_u64 v[36:37], s[18:19], 0, v[36:37]
	v_lshl_add_u64 v[48:49], v[146:147], 2, v[36:37]
	global_load_dwordx4 v[36:39], v[48:49], off
	global_load_dwordx4 v[40:43], v[48:49], off offset:16
	global_load_dwordx4 v[44:47], v[48:49], off offset:512
	global_load_dwordx4 v[190:193], v[48:49], off offset:528
	s_waitcnt vmcnt(3)
	v_pk_fma_f32 v[184:185], v[32:33], v[124:125], v[38:39]
	v_pk_fma_f32 v[186:187], v[30:31], v[122:123], v[36:37]
	s_waitcnt vmcnt(2)
	v_pk_fma_f32 v[180:181], v[28:29], v[128:129], v[42:43]
	v_pk_fma_f32 v[182:183], v[26:27], v[126:127], v[40:41]
	s_waitcnt vmcnt(1)
	v_pk_fma_f32 v[170:171], v[24:25], v[116:117], v[46:47]
	v_pk_fma_f32 v[172:173], v[22:23], v[114:115], v[44:45]
	s_waitcnt vmcnt(0)
	v_pk_fma_f32 v[174:175], v[20:21], v[120:121], v[192:193]
	v_pk_fma_f32 v[176:177], v[18:19], v[118:119], v[190:191]
	v_mul_f32_e32 v18, v187, v187
	v_mul_f32_e32 v19, v185, v185
	v_mul_f32_e32 v20, v183, v183
	v_mul_f32_e32 v21, v181, v181
	v_mul_f32_e32 v22, v173, v173
	v_mul_f32_e32 v23, v171, v171
	v_fmac_f32_e32 v18, v186, v186
	v_fmac_f32_e32 v19, v184, v184
	v_fmac_f32_e32 v20, v182, v182
	v_fmac_f32_e32 v21, v180, v180
	v_mul_f32_e32 v24, v177, v177
	v_mul_f32_e32 v25, v175, v175
	v_fmac_f32_e32 v22, v172, v172
	v_fmac_f32_e32 v23, v170, v170
	v_add_f32_e32 v18, v18, v19
	v_add_f32_e32 v19, v20, v21
	v_fmac_f32_e32 v24, v176, v176
	v_fmac_f32_e32 v25, v174, v174
	v_add_f32_e32 v20, v22, v23
	v_add_f32_e32 v18, v18, v19
	v_add_f32_e32 v18, v18, v20
	v_add_f32_e32 v19, v24, v25
	v_add_f32_e32 v18, v18, v19
	v_mov_b32_e32 v19, v18
	s_nop 1
	v_permlane16_swap_b32 v19, v18
	s_nop 1
	s_waitcnt lgkmcnt(0)
	v_add_f32_e32 v18, v18, v19
	v_mov_b32_e32 v19, v18
	s_nop 1
	v_permlane32_swap_b32 v19, v18
	s_nop 1
	s_and_saveexec_b64 s[20:21], vcc
	s_cbranch_execz .LBB0_968
	s_waitcnt lgkmcnt(0)
	v_add_f32_e32 v18, v18, v19
	ds_write_b32 v151, v18 offset:2560
.LBB0_968:
	s_or_b64 exec, exec, s[20:21]
	v_add_u32_e32 v18, 0xb0, v150
	s_waitcnt lgkmcnt(0)
	v_add_u32_e32 v19, 0xfffff0b0, v150
	v_cndmask_b32_e64 v20, v19, v18, s[4:5]
	v_ashrrev_i32_e32 v21, 31, v20
	v_lshlrev_b64 v[20:21], 13, v[20:21]
	v_lshl_add_u64 v[20:21], s[18:19], 0, v[20:21]
	v_lshl_add_u64 v[32:33], v[146:147], 2, v[20:21]
	global_load_dwordx4 v[20:23], v[32:33], off
	global_load_dwordx4 v[24:27], v[32:33], off offset:16
	global_load_dwordx4 v[28:31], v[32:33], off offset:512
	global_load_dwordx4 v[36:39], v[32:33], off offset:528
	s_waitcnt vmcnt(3)
	v_pk_fma_f32 v[190:191], v[16:17], v[124:125], v[22:23]
	v_pk_fma_f32 v[192:193], v[14:15], v[122:123], v[20:21]
	s_waitcnt vmcnt(2)
	v_pk_fma_f32 v[122:123], v[12:13], v[128:129], v[26:27]
	v_pk_fma_f32 v[124:125], v[10:11], v[126:127], v[24:25]
	s_waitcnt vmcnt(1)
	v_pk_fma_f32 v[116:117], v[8:9], v[116:117], v[30:31]
	v_pk_fma_f32 v[114:115], v[6:7], v[114:115], v[28:29]
	s_waitcnt vmcnt(0)
	v_pk_fma_f32 v[120:121], v[4:5], v[120:121], v[38:39]
	v_pk_fma_f32 v[118:119], v[2:3], v[118:119], v[36:37]
	v_mul_f32_e32 v2, v193, v193
	v_mul_f32_e32 v3, v191, v191
	v_mul_f32_e32 v4, v125, v125
	v_mul_f32_e32 v5, v123, v123
	v_mul_f32_e32 v6, v115, v115
	v_mul_f32_e32 v7, v117, v117
	v_fmac_f32_e32 v2, v192, v192
	v_fmac_f32_e32 v3, v190, v190
	v_fmac_f32_e32 v4, v124, v124
	v_fmac_f32_e32 v5, v122, v122
	v_mul_f32_e32 v8, v119, v119
	v_mul_f32_e32 v9, v121, v121
	v_fmac_f32_e32 v6, v114, v114
	v_fmac_f32_e32 v7, v116, v116
	v_add_f32_e32 v2, v2, v3
	v_add_f32_e32 v3, v4, v5
	v_fmac_f32_e32 v8, v118, v118
	v_fmac_f32_e32 v9, v120, v120
	v_add_f32_e32 v4, v6, v7
	v_add_f32_e32 v2, v2, v3
	v_add_f32_e32 v2, v2, v4
	v_add_f32_e32 v3, v8, v9
	v_add_f32_e32 v2, v2, v3
	v_mov_b32_e32 v0, v2
	s_nop 1
	v_permlane16_swap_b32 v0, v2
	s_nop 1
	s_waitcnt lgkmcnt(0)
	v_add_f32_e32 v0, v2, v0
	v_mov_b32_e32 v2, v0
	s_nop 1
	v_permlane32_swap_b32 v2, v0
	s_nop 1
	s_and_saveexec_b64 s[4:5], vcc
	s_cbranch_execz .LBB0_970
	s_waitcnt lgkmcnt(0)
	v_add_f32_e32 v0, v0, v2
	ds_write_b32 v151, v0 offset:2816

.LBB0_1207:
	s_mul_i32 s5, s56, 0x24000
	s_mul_hi_u32 s4, s56, 0x24000
	s_add_u32 s5, s26, s5
	s_addc_u32 s4, s27, s4
	s_add_u32 s22, s5, 0x580000
	s_addc_u32 s23, s4, 0
	s_lshl_b32 s4, s33, 5
	s_add_u32 s8, s26, 0x15e12000
	s_addc_u32 s9, s27, 0
	s_add_u32 s6, s26, 0x16e12000
	s_addc_u32 s7, s27, 0
	s_lshl_b32 s20, s39, 8
	s_lshl_b32 s18, s16, 8
	v_lshrrev_b32_e32 v0, 1, v213
	s_add_i32 s5, s20, s34
	s_or_b32 s4, s18, s4
	v_and_or_b32 v208, v0, 24, s4
	s_cmp_lt_i32 s39, 24
	s_movk_i32 s4, 0x3000
	s_cselect_b32 s18, s4, 0x6000
	s_cmp_lt_i32 s39, 16
	s_cselect_b64 vcc, -1, 0
	v_or_b32_e32 v210, s5, v212
	s_and_b64 s[4:5], vcc, exec
	s_cselect_b32 s18, 0, s18
	v_lshlrev_b32_e32 v0, 11, v210
	s_cselect_b32 s5, s9, s7
	s_cselect_b32 s4, s8, s6
	s_lshl_b32 s21, s18, 2
	v_add_u32_e32 v130, 0x7f800000, v0
	s_add_u32 s6, s22, s21
	v_cndmask_b32_e32 v0, v130, v0, vcc
	s_addc_u32 s7, s23, 0
	v_ashrrev_i32_e32 v209, 31, v208
	v_add_lshl_u32 v146, v0, v208, 1
	v_lshl_add_u64 v[130:131], v[208:209], 2, s[6:7]
	s_mov_b32 s6, 0xa000
	s_barrier
	global_load_dwordx4 v[202:205], v146, s[4:5]
	v_add_co_u32_e32 v132, vcc, s6, v130
	s_mov_b64 s[6:7], 0xa000
	s_nop 0
	v_addc_co_u32_e32 v133, vcc, 0, v131, vcc
	global_load_dwordx4 v[216:219], v146, s[4:5] offset:256
	global_load_dwordx4 v[142:145], v[132:133], off
	v_lshl_add_u64 v[134:135], v[130:131], 0, s[6:7]
	global_load_dwordx4 v[138:141], v[134:135], off offset:16
	global_load_dwordx4 v[130:133], v[134:135], off offset:528
	s_nop 0
	global_load_dwordx4 v[134:137], v[134:135], off offset:512
	v_add_u32_e32 v147, 0x10000, v146
	v_or_b32_e32 v148, 0x100, v147
	global_load_dwordx4 v[198:201], v147, s[4:5]
	global_load_dwordx4 v[194:197], v148, s[4:5]
	v_add_u32_e32 v147, 0x20000, v146
	v_add_u32_e32 v146, 0x30000, v146
	v_add_u32_e32 v0, 0x40000, v0
	v_or_b32_e32 v148, 0x100, v147
	global_load_dwordx4 v[190:193], v147, s[4:5]
	global_load_dwordx4 v[186:189], v148, s[4:5]
	v_or_b32_e32 v147, 0x100, v146
	global_load_dwordx4 v[178:181], v146, s[4:5]
	global_load_dwordx4 v[174:177], v147, s[4:5]
	v_add_lshl_u32 v146, v0, v208, 1
	v_or_b32_e32 v147, 0x100, v146
	global_load_dwordx4 v[182:185], v146, s[4:5]
	global_load_dwordx4 v[170:173], v147, s[4:5]
	v_or_b32_e32 v146, 0x8000, v0
	v_add_lshl_u32 v146, v146, v208, 1
	v_or_b32_e32 v147, 0x100, v146
	global_load_dwordx4 v[166:169], v146, s[4:5]
	global_load_dwordx4 v[162:165], v147, s[4:5]
	v_or_b32_e32 v146, 0x10000, v0
	v_or_b32_e32 v0, 0x18000, v0
	v_add_lshl_u32 v146, v146, v208, 1
	v_add_lshl_u32 v0, v0, v208, 1
	v_or_b32_e32 v147, 0x100, v146
	global_load_dwordx4 v[158:161], v146, s[4:5]
	global_load_dwordx4 v[154:157], v147, s[4:5]
	v_or_b32_e32 v146, 0x100, v0
	global_load_dwordx4 v[150:153], v0, s[4:5]
	s_nop 0
	global_load_dwordx4 v[146:149], v146, s[4:5]
	v_and_b32_e32 v214, 63, v213
	s_lshl_b32 s4, s33, 2
	s_add_i32 s4, s4, 0
	v_cmp_gt_u32_e32 vcc, 16, v214
	v_lshl_add_u32 v211, v211, 4, s4
	s_waitcnt vmcnt(0)
	v_lshlrev_b32_e32 v206, 16, v202
	v_and_b32_e32 v207, 0xffff0000, v202
	v_lshlrev_b32_e32 v202, 16, v203
	v_and_b32_e32 v203, 0xffff0000, v203
	v_lshlrev_b32_e32 v220, 16, v204
	v_and_b32_e32 v221, 0xffff0000, v204
	v_lshlrev_b32_e32 v204, 16, v205
	v_and_b32_e32 v205, 0xffff0000, v205
	v_pk_fma_f32 v[128:129], v[128:129], v[144:145], v[202:203]
	v_pk_fma_f32 v[126:127], v[126:127], v[142:143], v[206:207]
	v_pk_fma_f32 v[124:125], v[124:125], v[140:141], v[204:205]
	v_pk_fma_f32 v[122:123], v[122:123], v[138:139], v[220:221]
	v_mul_f32_e32 v0, v127, v127
	v_mul_f32_e32 v202, v129, v129
	v_mul_f32_e32 v203, v123, v123
	v_mul_f32_e32 v204, v125, v125
	v_fmac_f32_e32 v0, v126, v126
	v_fmac_f32_e32 v202, v128, v128
	v_fmac_f32_e32 v203, v122, v122
	v_fmac_f32_e32 v204, v124, v124
	v_add_f32_e32 v0, v0, v202
	v_add_f32_e32 v202, v203, v204
	v_lshlrev_b32_e32 v222, 16, v216
	v_add_f32_e32 v0, v0, v202
	v_and_b32_e32 v223, 0xffff0000, v216
	v_lshlrev_b32_e32 v202, 16, v217
	v_and_b32_e32 v203, 0xffff0000, v217
	v_pk_fma_f32 v[120:121], v[120:121], v[136:137], v[202:203]
	v_pk_fma_f32 v[118:119], v[118:119], v[134:135], v[222:223]
	v_lshlrev_b32_e32 v204, 16, v218
	v_and_b32_e32 v205, 0xffff0000, v218
	v_lshlrev_b32_e32 v206, 16, v219
	v_and_b32_e32 v207, 0xffff0000, v219
	v_mul_f32_e32 v202, v119, v119
	v_mul_f32_e32 v203, v121, v121
	v_pk_fma_f32 v[116:117], v[116:117], v[132:133], v[206:207]
	v_pk_fma_f32 v[114:115], v[114:115], v[130:131], v[204:205]
	v_fmac_f32_e32 v202, v118, v118
	v_fmac_f32_e32 v203, v120, v120
	v_add_f32_e32 v202, v202, v203
	v_mul_f32_e32 v203, v115, v115
	v_mul_f32_e32 v204, v117, v117
	v_fmac_f32_e32 v203, v114, v114
	v_fmac_f32_e32 v204, v116, v116
	v_add_f32_e32 v203, v203, v204
	v_add_f32_e32 v202, v202, v203
	v_lshlrev_b32_e32 v203, 2, v214
	v_add_f32_e32 v202, v0, v202
	v_xor_b32_e32 v0, 64, v203
	v_mov_b32_e32 v204, v202
	s_nop 1
	v_permlane16_swap_b32 v204, v202
	s_nop 1
	v_xor_b32_e32 v215, 0x80, v203
	s_waitcnt lgkmcnt(0)
	v_add_f32_e32 v216, v202, v204
	v_mov_b32_e32 v217, v216
	s_nop 1
	v_permlane32_swap_b32 v217, v216
	s_nop 1
	s_and_saveexec_b64 s[4:5], vcc
	s_cbranch_execz .LBB0_1209
	s_waitcnt lgkmcnt(0)
	v_add_f32_e32 v202, v216, v217
	ds_write_b32 v211, v202

.LBB0_1211:
	s_or_b64 exec, exec, s[4:5]
	v_lshlrev_b32_e32 v194, 16, v190
	s_waitcnt lgkmcnt(0)
	v_and_b32_e32 v195, 0xffff0000, v190
	v_lshlrev_b32_e32 v190, 16, v191
	v_and_b32_e32 v191, 0xffff0000, v191
	v_lshlrev_b32_e32 v196, 16, v192
	v_and_b32_e32 v197, 0xffff0000, v192
	v_lshlrev_b32_e32 v198, 16, v193
	v_and_b32_e32 v199, 0xffff0000, v193
	v_pk_fma_f32 v[100:101], v[100:101], v[144:145], v[190:191]
	v_pk_fma_f32 v[192:193], v[98:99], v[142:143], v[194:195]
	v_pk_fma_f32 v[190:191], v[90:91], v[138:139], v[196:197]
	v_mul_f32_e32 v90, v193, v193
	v_mul_f32_e32 v91, v101, v101
	v_pk_fma_f32 v[98:99], v[92:93], v[140:141], v[198:199]
	v_fmac_f32_e32 v90, v192, v192
	v_fmac_f32_e32 v91, v100, v100
	v_add_f32_e32 v90, v90, v91
	v_mul_f32_e32 v91, v191, v191
	v_mul_f32_e32 v92, v99, v99
	v_fmac_f32_e32 v91, v190, v190
	v_fmac_f32_e32 v92, v98, v98
	v_add_f32_e32 v91, v91, v92
	v_add_f32_e32 v194, v90, v91
	v_lshlrev_b32_e32 v90, 16, v186
	v_and_b32_e32 v91, 0xffff0000, v186
	v_lshlrev_b32_e32 v92, 16, v187
	v_and_b32_e32 v93, 0xffff0000, v187
	v_pk_fma_f32 v[88:89], v[88:89], v[136:137], v[92:93]
	v_pk_fma_f32 v[86:87], v[86:87], v[134:135], v[90:91]
	v_lshlrev_b32_e32 v186, 16, v188
	v_and_b32_e32 v187, 0xffff0000, v188
	v_lshlrev_b32_e32 v188, 16, v189
	v_and_b32_e32 v189, 0xffff0000, v189
	v_mul_f32_e32 v90, v87, v87
	v_mul_f32_e32 v91, v89, v89
	v_pk_fma_f32 v[80:81], v[80:81], v[132:133], v[188:189]
	v_pk_fma_f32 v[78:79], v[78:79], v[130:131], v[186:187]
	v_fmac_f32_e32 v90, v86, v86
	v_fmac_f32_e32 v91, v88, v88
	v_add_f32_e32 v90, v90, v91
	v_mul_f32_e32 v91, v79, v79
	v_mul_f32_e32 v92, v81, v81
	v_fmac_f32_e32 v91, v78, v78
	v_fmac_f32_e32 v92, v80, v80
	v_add_f32_e32 v91, v91, v92
	v_add_f32_e32 v90, v90, v91
	v_add_f32_e32 v90, v194, v90
	v_mov_b32_e32 v91, v90
	s_nop 1
	v_permlane16_swap_b32 v91, v90
	s_nop 1
	s_waitcnt lgkmcnt(0)
	v_add_f32_e32 v90, v90, v91
	v_mov_b32_e32 v91, v90
	s_nop 1
	v_permlane32_swap_b32 v91, v90
	s_nop 1
	s_and_saveexec_b64 s[4:5], vcc
	s_cbranch_execz .LBB0_1213
	s_waitcnt lgkmcnt(0)
	v_add_f32_e32 v90, v90, v91
	ds_write_b32 v211, v90 offset:512
.LBB0_1213:
	s_or_b64 exec, exec, s[4:5]
	v_lshlrev_b32_e32 v90, 16, v178
	s_waitcnt lgkmcnt(0)
	v_and_b32_e32 v91, 0xffff0000, v178
	v_lshlrev_b32_e32 v92, 16, v179
	v_and_b32_e32 v93, 0xffff0000, v179
	v_lshlrev_b32_e32 v186, 16, v180
	v_and_b32_e32 v187, 0xffff0000, v180
	v_lshlrev_b32_e32 v178, 16, v181
	v_and_b32_e32 v179, 0xffff0000, v181
	v_pk_fma_f32 v[180:181], v[84:85], v[144:145], v[92:93]
	v_pk_fma_f32 v[188:189], v[82:83], v[142:143], v[90:91]
	v_pk_fma_f32 v[186:187], v[74:75], v[138:139], v[186:187]
	v_mul_f32_e32 v74, v189, v189
	v_mul_f32_e32 v75, v181, v181
	v_pk_fma_f32 v[178:179], v[76:77], v[140:141], v[178:179]
	v_fmac_f32_e32 v74, v188, v188
	v_fmac_f32_e32 v75, v180, v180
	v_add_f32_e32 v74, v74, v75
	v_mul_f32_e32 v75, v187, v187
	v_mul_f32_e32 v76, v179, v179
	v_fmac_f32_e32 v75, v186, v186
	v_fmac_f32_e32 v76, v178, v178
	v_add_f32_e32 v75, v75, v76
	v_add_f32_e32 v90, v74, v75
	v_lshlrev_b32_e32 v74, 16, v174
	v_and_b32_e32 v75, 0xffff0000, v174
	v_lshlrev_b32_e32 v76, 16, v175
	v_and_b32_e32 v77, 0xffff0000, v175
	v_pk_fma_f32 v[72:73], v[72:73], v[136:137], v[76:77]
	v_pk_fma_f32 v[70:71], v[70:71], v[134:135], v[74:75]
	v_lshlrev_b32_e32 v82, 16, v176
	v_and_b32_e32 v83, 0xffff0000, v176
	v_lshlrev_b32_e32 v84, 16, v177
	v_and_b32_e32 v85, 0xffff0000, v177
	v_mul_f32_e32 v74, v71, v71
	v_mul_f32_e32 v75, v73, v73
	v_pk_fma_f32 v[68:69], v[68:69], v[132:133], v[84:85]
	v_pk_fma_f32 v[66:67], v[66:67], v[130:131], v[82:83]
	v_fmac_f32_e32 v74, v70, v70
	v_fmac_f32_e32 v75, v72, v72
	v_add_f32_e32 v74, v74, v75
	v_mul_f32_e32 v75, v67, v67
	v_mul_f32_e32 v76, v69, v69
	v_fmac_f32_e32 v75, v66, v66
	v_fmac_f32_e32 v76, v68, v68
	v_add_f32_e32 v75, v75, v76
	v_add_f32_e32 v74, v74, v75
	v_add_f32_e32 v74, v90, v74
	v_mov_b32_e32 v75, v74
	s_nop 1
	v_permlane16_swap_b32 v75, v74
	s_nop 1
	s_waitcnt lgkmcnt(0)
	v_add_f32_e32 v74, v74, v75
	v_mov_b32_e32 v75, v74
	s_nop 1
	v_permlane32_swap_b32 v75, v74
	s_nop 1
	s_and_saveexec_b64 s[4:5], vcc
	s_cbranch_execz .LBB0_1215
	s_waitcnt lgkmcnt(0)
	v_add_f32_e32 v74, v74, v75
	ds_write_b32 v211, v74 offset:768
.LBB0_1215:
	s_or_b64 exec, exec, s[4:5]
	v_lshlrev_b32_e32 v74, 16, v182
	s_waitcnt lgkmcnt(0)
	v_and_b32_e32 v75, 0xffff0000, v182
	v_lshlrev_b32_e32 v76, 16, v183
	v_and_b32_e32 v77, 0xffff0000, v183
	v_lshlrev_b32_e32 v82, 16, v184
	v_and_b32_e32 v83, 0xffff0000, v184
	v_lshlrev_b32_e32 v84, 16, v185
	v_and_b32_e32 v85, 0xffff0000, v185
	v_pk_fma_f32 v[176:177], v[64:65], v[144:145], v[76:77]
	v_pk_fma_f32 v[184:185], v[62:63], v[142:143], v[74:75]
	v_pk_fma_f32 v[182:183], v[58:59], v[138:139], v[82:83]
	v_mul_f32_e32 v58, v185, v185
	v_mul_f32_e32 v59, v177, v177
	v_pk_fma_f32 v[174:175], v[60:61], v[140:141], v[84:85]
	v_fmac_f32_e32 v58, v184, v184
	v_fmac_f32_e32 v59, v176, v176
	v_add_f32_e32 v58, v58, v59
	v_mul_f32_e32 v59, v183, v183
	v_mul_f32_e32 v60, v175, v175
	v_fmac_f32_e32 v59, v182, v182
	v_fmac_f32_e32 v60, v174, v174
	v_add_f32_e32 v59, v59, v60
	v_add_f32_e32 v74, v58, v59
	v_lshlrev_b32_e32 v58, 16, v170
	v_and_b32_e32 v59, 0xffff0000, v170
	v_lshlrev_b32_e32 v60, 16, v171
	v_and_b32_e32 v61, 0xffff0000, v171
	v_pk_fma_f32 v[56:57], v[56:57], v[136:137], v[60:61]
	v_pk_fma_f32 v[54:55], v[54:55], v[134:135], v[58:59]
	v_lshlrev_b32_e32 v62, 16, v172
	v_and_b32_e32 v63, 0xffff0000, v172
	v_lshlrev_b32_e32 v64, 16, v173
	v_and_b32_e32 v65, 0xffff0000, v173
	v_mul_f32_e32 v58, v55, v55
	v_mul_f32_e32 v59, v57, v57
	v_pk_fma_f32 v[48:49], v[48:49], v[132:133], v[64:65]
	v_pk_fma_f32 v[46:47], v[46:47], v[130:131], v[62:63]
	v_fmac_f32_e32 v58, v54, v54
	v_fmac_f32_e32 v59, v56, v56
	v_add_f32_e32 v58, v58, v59
	v_mul_f32_e32 v59, v47, v47
	v_mul_f32_e32 v60, v49, v49
	v_fmac_f32_e32 v59, v46, v46
	v_fmac_f32_e32 v60, v48, v48
	v_add_f32_e32 v59, v59, v60
	v_add_f32_e32 v58, v58, v59
	v_add_f32_e32 v58, v74, v58
	v_mov_b32_e32 v59, v58
	s_nop 1
	v_permlane16_swap_b32 v59, v58
	s_nop 1
	s_waitcnt lgkmcnt(0)
	v_add_f32_e32 v58, v58, v59
	v_mov_b32_e32 v59, v58
	s_nop 1
	v_permlane32_swap_b32 v59, v58
	s_nop 1
	s_and_saveexec_b64 s[4:5], vcc
	s_cbranch_execz .LBB0_1217
	s_waitcnt lgkmcnt(0)
	v_add_f32_e32 v58, v58, v59
	ds_write_b32 v211, v58 offset:2048
.LBB0_1217:
	s_or_b64 exec, exec, s[4:5]
	v_lshlrev_b32_e32 v58, 16, v166
	s_waitcnt lgkmcnt(0)
	v_and_b32_e32 v59, 0xffff0000, v166
	v_lshlrev_b32_e32 v60, 16, v167
	v_and_b32_e32 v61, 0xffff0000, v167
	v_lshlrev_b32_e32 v62, 16, v168
	v_and_b32_e32 v63, 0xffff0000, v168
	v_lshlrev_b32_e32 v64, 16, v169
	v_and_b32_e32 v65, 0xffff0000, v169
	v_pk_fma_f32 v[168:169], v[52:53], v[144:145], v[60:61]
	v_pk_fma_f32 v[172:173], v[50:51], v[142:143], v[58:59]
	v_pk_fma_f32 v[170:171], v[42:43], v[138:139], v[62:63]
	v_mul_f32_e32 v42, v173, v173
	v_mul_f32_e32 v43, v169, v169
	v_pk_fma_f32 v[166:167], v[44:45], v[140:141], v[64:65]
	v_fmac_f32_e32 v42, v172, v172
	v_fmac_f32_e32 v43, v168, v168
	v_add_f32_e32 v42, v42, v43
	v_mul_f32_e32 v43, v171, v171
	v_mul_f32_e32 v44, v167, v167
	v_fmac_f32_e32 v43, v170, v170
	v_fmac_f32_e32 v44, v166, v166
	v_add_f32_e32 v43, v43, v44
	v_add_f32_e32 v60, v42, v43
	v_lshlrev_b32_e32 v42, 16, v162
	v_and_b32_e32 v43, 0xffff0000, v162
	v_lshlrev_b32_e32 v44, 16, v163
	v_and_b32_e32 v45, 0xffff0000, v163
	v_lshlrev_b32_e32 v50, 16, v164
	v_and_b32_e32 v51, 0xffff0000, v164
	v_pk_fma_f32 v[44:45], v[40:41], v[136:137], v[44:45]
	v_pk_fma_f32 v[52:53], v[38:39], v[134:135], v[42:43]
	v_lshlrev_b32_e32 v58, 16, v165
	v_and_b32_e32 v59, 0xffff0000, v165
	v_pk_fma_f32 v[50:51], v[30:31], v[130:131], v[50:51]
	v_mul_f32_e32 v30, v53, v53
	v_mul_f32_e32 v31, v45, v45
	v_pk_fma_f32 v[42:43], v[32:33], v[132:133], v[58:59]
	v_fmac_f32_e32 v30, v52, v52
	v_fmac_f32_e32 v31, v44, v44
	v_add_f32_e32 v30, v30, v31
	v_mul_f32_e32 v31, v51, v51
	v_mul_f32_e32 v32, v43, v43
	v_fmac_f32_e32 v31, v50, v50
	v_fmac_f32_e32 v32, v42, v42
	v_add_f32_e32 v31, v31, v32
	v_add_f32_e32 v30, v30, v31
	v_add_f32_e32 v30, v60, v30
	v_mov_b32_e32 v31, v30
	s_nop 1
	v_permlane16_swap_b32 v31, v30
	s_nop 1
	s_waitcnt lgkmcnt(0)
	v_add_f32_e32 v30, v30, v31
	v_mov_b32_e32 v31, v30
	s_nop 1
	v_permlane32_swap_b32 v31, v30
	s_nop 1
	s_and_saveexec_b64 s[4:5], vcc
	s_cbranch_execz .LBB0_1219
	s_waitcnt lgkmcnt(0)
	v_add_f32_e32 v30, v30, v31
	ds_write_b32 v211, v30 offset:2304
.LBB0_1219:
	s_or_b64 exec, exec, s[4:5]
	v_lshlrev_b32_e32 v30, 16, v158
	s_waitcnt lgkmcnt(0)
	v_and_b32_e32 v31, 0xffff0000, v158
	v_lshlrev_b32_e32 v32, 16, v159
	v_and_b32_e32 v33, 0xffff0000, v159
	v_lshlrev_b32_e32 v38, 16, v160
	v_and_b32_e32 v39, 0xffff0000, v160
	v_lshlrev_b32_e32 v40, 16, v161
	v_and_b32_e32 v41, 0xffff0000, v161
	v_pk_fma_f32 v[160:161], v[36:37], v[144:145], v[32:33]
	v_pk_fma_f32 v[164:165], v[34:35], v[142:143], v[30:31]
	v_pk_fma_f32 v[162:163], v[26:27], v[138:139], v[38:39]
	v_mul_f32_e32 v26, v165, v165
	v_mul_f32_e32 v27, v161, v161
	v_pk_fma_f32 v[158:159], v[28:29], v[140:141], v[40:41]
	v_fmac_f32_e32 v26, v164, v164
	v_fmac_f32_e32 v27, v160, v160
	v_add_f32_e32 v26, v26, v27
	v_mul_f32_e32 v27, v163, v163
	v_mul_f32_e32 v28, v159, v159
	v_fmac_f32_e32 v27, v162, v162
	v_fmac_f32_e32 v28, v158, v158
	v_add_f32_e32 v27, v27, v28
	v_add_f32_e32 v34, v26, v27
	v_lshlrev_b32_e32 v26, 16, v154
	v_and_b32_e32 v27, 0xffff0000, v154
	v_lshlrev_b32_e32 v28, 16, v155
	v_and_b32_e32 v29, 0xffff0000, v155
	v_lshlrev_b32_e32 v30, 16, v156
	v_and_b32_e32 v31, 0xffff0000, v156
	v_pk_fma_f32 v[60:61], v[24:25], v[136:137], v[28:29]
	v_pk_fma_f32 v[64:65], v[22:23], v[134:135], v[26:27]
	v_lshlrev_b32_e32 v32, 16, v157
	v_and_b32_e32 v33, 0xffff0000, v157
	v_pk_fma_f32 v[62:63], v[14:15], v[130:131], v[30:31]
	v_mul_f32_e32 v14, v65, v65
	v_mul_f32_e32 v15, v61, v61
	v_pk_fma_f32 v[58:59], v[16:17], v[132:133], v[32:33]
	v_fmac_f32_e32 v14, v64, v64
	v_fmac_f32_e32 v15, v60, v60
	v_add_f32_e32 v14, v14, v15
	v_mul_f32_e32 v15, v63, v63
	v_mul_f32_e32 v16, v59, v59
	v_fmac_f32_e32 v15, v62, v62
	v_fmac_f32_e32 v16, v58, v58
	v_add_f32_e32 v15, v15, v16
	v_add_f32_e32 v14, v14, v15
	v_add_f32_e32 v14, v34, v14
	v_mov_b32_e32 v15, v14
	s_nop 1
	v_permlane16_swap_b32 v15, v14
	s_nop 1
	s_waitcnt lgkmcnt(0)
	v_add_f32_e32 v14, v14, v15
	v_mov_b32_e32 v15, v14
	s_nop 1
	v_permlane32_swap_b32 v15, v14
	s_nop 1
	s_and_saveexec_b64 s[4:5], vcc
	s_cbranch_execz .LBB0_1221
	s_waitcnt lgkmcnt(0)
	v_add_f32_e32 v14, v14, v15
	ds_write_b32 v211, v14 offset:2560
.LBB0_1221:
	s_or_b64 exec, exec, s[4:5]
	v_lshlrev_b32_e32 v14, 16, v150
	s_waitcnt lgkmcnt(0)
	v_and_b32_e32 v15, 0xffff0000, v150
	v_lshlrev_b32_e32 v16, 16, v151
	v_and_b32_e32 v17, 0xffff0000, v151
	v_lshlrev_b32_e32 v22, 16, v152
	v_and_b32_e32 v23, 0xffff0000, v152
	v_pk_fma_f32 v[144:145], v[20:21], v[144:145], v[16:17]
	v_pk_fma_f32 v[142:143], v[18:19], v[142:143], v[14:15]
	v_lshlrev_b32_e32 v24, 16, v153
	v_and_b32_e32 v25, 0xffff0000, v153
	v_pk_fma_f32 v[138:139], v[10:11], v[138:139], v[22:23]
	v_mul_f32_e32 v10, v143, v143
	v_mul_f32_e32 v11, v145, v145
	v_pk_fma_f32 v[140:141], v[12:13], v[140:141], v[24:25]
	v_fmac_f32_e32 v10, v142, v142
	v_fmac_f32_e32 v11, v144, v144
	v_add_f32_e32 v10, v10, v11
	v_mul_f32_e32 v11, v139, v139
	v_mul_f32_e32 v12, v141, v141
	v_fmac_f32_e32 v11, v138, v138
	v_fmac_f32_e32 v12, v140, v140
	v_add_f32_e32 v11, v11, v12
	v_add_f32_e32 v18, v10, v11
	v_lshlrev_b32_e32 v10, 16, v146
	v_and_b32_e32 v11, 0xffff0000, v146
	v_lshlrev_b32_e32 v12, 16, v147
	v_and_b32_e32 v13, 0xffff0000, v147
	v_lshlrev_b32_e32 v14, 16, v148
	v_and_b32_e32 v15, 0xffff0000, v148
	v_pk_fma_f32 v[76:77], v[8:9], v[136:137], v[12:13]
	v_pk_fma_f32 v[84:85], v[6:7], v[134:135], v[10:11]
	v_lshlrev_b32_e32 v16, 16, v149
	v_and_b32_e32 v17, 0xffff0000, v149
	v_pk_fma_f32 v[82:83], v[2:3], v[130:131], v[14:15]
	v_mul_f32_e32 v2, v85, v85
	v_mul_f32_e32 v3, v77, v77
	v_pk_fma_f32 v[74:75], v[4:5], v[132:133], v[16:17]
	v_fmac_f32_e32 v2, v84, v84
	v_fmac_f32_e32 v3, v76, v76
	v_add_f32_e32 v2, v2, v3
	v_mul_f32_e32 v3, v83, v83
	v_mul_f32_e32 v4, v75, v75
	v_fmac_f32_e32 v3, v82, v82
	v_fmac_f32_e32 v4, v74, v74
	v_add_f32_e32 v3, v3, v4
	v_add_f32_e32 v2, v2, v3
	v_add_f32_e32 v2, v18, v2
	v_mov_b32_e32 v0, v2
	s_nop 1
	v_permlane16_swap_b32 v0, v2
	s_nop 1
	s_waitcnt lgkmcnt(0)
	v_add_f32_e32 v0, v2, v0
	v_mov_b32_e32 v2, v0
	s_nop 1
	v_permlane32_swap_b32 v2, v0
	s_nop 1
	s_and_saveexec_b64 s[4:5], vcc
	s_cbranch_execz .LBB0_1223
	s_waitcnt lgkmcnt(0)
	v_add_f32_e32 v0, v0, v2
	ds_write_b32 v211, v0 offset:2816
